# GEMM loops: removed the redundant back-to-back s_setprio 0 / s_setprio 1 pair in the middle of each 32-MFMA phase
# baseline (speedup 1.0000x reference)
; #define PG8_STAGE(bufoff, gbase, voff) do { _Pragma("unroll") for (int _i = 0; _i < 2; ++_i) \
;         __builtin_amdgcn_global_load_lds((const unsigned*)((const char*)(gbase) + (voff)[_i]), (LAS unsigned*)(lds + (bufoff) + ldsw + _i * 8192), 16, 0, 0); } while (0)
; #define PG8_LDA(dst, b, h) do { _Pragma("unroll") for (int m = 0; m < 4; ++m) _Pragma("unroll") for (int k = 0; k < 2; ++k) dst[m][k] = *(const LAS bf16x8*)(lds + PG8_SA(b, h) + aoff + m * 2048 + k * 1024); } while (0)
; #define PG8_LDB(dst, b, h) do { _Pragma("unroll") for (int n = 0; n < 2; ++n) _Pragma("unroll") for (int k = 0; k < 2; ++k) dst[n][k] = *(const LAS bf16x8*)(lds + PG8_SB(b, h) + boff + n * 2048 + k * 1024); } while (0)
; #define PG8_MMA(ai, bj, At, Bt) do { __builtin_amdgcn_s_setprio(1); _Pragma("unroll") for (int m = 0; m < 4; ++m) _Pragma("unroll") for (int n = 0; n < 2; ++n) _Pragma("unroll") for (int k = 0; k < 2; ++k) \
;         acc[ai][bj][m][n] = __builtin_amdgcn_mfma_f32_16x16x32_bf16(Bt[n][k], At[m][k], acc[ai][bj][m][n], 0, 0, 0); __builtin_amdgcn_s_setprio(0); } while (0)
; #define PG8_WAIT_V(n) asm volatile("s_waitcnt vmcnt(" #n ")" ::: "memory")
; #define PG8_WAIT_L(n) asm volatile("s_waitcnt lgkmcnt(" #n ")" ::: "memory")
; #define PG8_BAR __builtin_amdgcn_s_barrier()
; #define PG8_SCHED __builtin_amdgcn_sched_barrier(0)
; template <class Epi, class Sched, bool ALIGN_EPI = false, bool SP2 = false>
; DI void gemm_phase(LAS unsigned char* lds, const Gemm g, const Sched& S, const Epi& E, const int tidx) {
;     ...
;             PG8_LDB(B0, 0, 0); PG8_LDB(B1, 0, 1); PG8_SCHED; PG8_LDA(At, 0, 0); PG8_STAGE(PG8_SA(1, 1), a1 + hstepA, voffA);
;             PG8_WAIT_V(8); PG8_WAIT_L(0); PG8_BAR; PG8_MMA(0, 0, At, B0); PG8_MMA(0, 1, At, B1); PG8_BAR; PG8_SCHED;
;             PG8_LDA(At, 0, 1); PG8_STAGE(PG8_SB(0, 0), b2, voffB); PG8_STAGE(PG8_SB(0, 1), b2 + hstepB, voffB); PG8_STAGE(PG8_SA(0, 0), a2, voffA);
;             PG8_WAIT_V(8); PG8_WAIT_L(0); PG8_BAR; PG8_MMA(1, 0, At, B0); PG8_MMA(1, 1, At, B1); PG8_BAR; PG8_SCHED;
.LBB0_39:
	s_add_u32 s24, s22, 0xffe00080
	s_addc_u32 s25, s23, -1
	s_add_i32 s91, 0, 0x10000
	s_cmpk_eq_i32 s83, 0x7c
	s_cselect_b32 s27, s5, s25
	s_cselect_b32 s26, s15, s24
	s_cselect_b32 s25, s13, s82
	s_cselect_b32 s24, s21, s57
	s_add_i32 s97, 0, 0x14000
	v_add_u32_e32 v140, s91, v221
	v_add_u32_e32 v156, s97, v221
	ds_read_b128 v[128:131], v140
	ds_read_b128 v[132:135], v140 offset:1024
	ds_read_b128 v[136:139], v140 offset:2048
	ds_read_b128 v[140:143], v140 offset:3072
	ds_read_b128 v[144:147], v156
	ds_read_b128 v[148:151], v156 offset:1024
	ds_read_b128 v[152:155], v156 offset:2048
	ds_read_b128 v[156:159], v156 offset:3072
	v_lshl_add_u64 v[202:203], s[22:23], 0, v[190:191]
	s_add_i32 m0, s30, 0xc000
	ds_read_b128 v[160:163], v235
	ds_read_b128 v[164:167], v235 offset:1024
	ds_read_b128 v[168:171], v235 offset:2048
	ds_read_b128 v[172:175], v235 offset:3072
	ds_read_b128 v[176:179], v235 offset:4096
	ds_read_b128 v[180:183], v235 offset:5120
	ds_read_b128 v[194:197], v235 offset:6144
	ds_read_b128 v[198:201], v235 offset:7168
	global_load_lds_dwordx4 v[202:203], off
	v_lshl_add_u64 v[202:203], s[22:23], 0, v[192:193]
	s_add_i32 m0, s30, 0xe000
	s_nop 0
	global_load_lds_dwordx4 v[202:203], off
	s_waitcnt vmcnt(8)
	s_waitcnt lgkmcnt(0)
	s_barrier
	s_setprio 1
	s_waitcnt lgkmcnt(0)
	v_mfma_f32_16x16x32_bf16 v[124:127], v[128:131], v[160:163], v[124:127]
	v_mfma_f32_16x16x32_bf16 v[120:123], v[136:139], v[160:163], v[120:123]
	v_mfma_f32_16x16x32_bf16 v[108:111], v[128:131], v[168:171], v[108:111]
	v_mfma_f32_16x16x32_bf16 v[104:107], v[136:139], v[168:171], v[104:107]
	v_mfma_f32_16x16x32_bf16 v[92:95], v[128:131], v[176:179], v[92:95]
	v_mfma_f32_16x16x32_bf16 v[88:91], v[136:139], v[176:179], v[88:91]
	v_mfma_f32_16x16x32_bf16 v[76:79], v[128:131], v[194:197], v[76:79]
	v_mfma_f32_16x16x32_bf16 v[72:75], v[136:139], v[194:197], v[72:75]
	v_mfma_f32_16x16x32_bf16 v[124:127], v[132:135], v[164:167], v[124:127]
	v_mfma_f32_16x16x32_bf16 v[120:123], v[140:143], v[164:167], v[120:123]
	v_mfma_f32_16x16x32_bf16 v[108:111], v[132:135], v[172:175], v[108:111]
	v_mfma_f32_16x16x32_bf16 v[104:107], v[140:143], v[172:175], v[104:107]
	v_mfma_f32_16x16x32_bf16 v[92:95], v[132:135], v[180:183], v[92:95]
	v_mfma_f32_16x16x32_bf16 v[88:91], v[140:143], v[180:183], v[88:91]
	v_mfma_f32_16x16x32_bf16 v[76:79], v[132:135], v[198:201], v[76:79]
	v_mfma_f32_16x16x32_bf16 v[72:75], v[140:143], v[198:201], v[72:75]
	v_mfma_f32_16x16x32_bf16 v[116:119], v[144:147], v[160:163], v[116:119]
	v_mfma_f32_16x16x32_bf16 v[112:115], v[152:155], v[160:163], v[112:115]
	v_mfma_f32_16x16x32_bf16 v[100:103], v[144:147], v[168:171], v[100:103]
	v_mfma_f32_16x16x32_bf16 v[96:99], v[152:155], v[168:171], v[96:99]
	v_mfma_f32_16x16x32_bf16 v[84:87], v[144:147], v[176:179], v[84:87]
	v_mfma_f32_16x16x32_bf16 v[80:83], v[152:155], v[176:179], v[80:83]
	v_mfma_f32_16x16x32_bf16 v[68:71], v[144:147], v[194:197], v[68:71]
	v_mfma_f32_16x16x32_bf16 v[64:67], v[152:155], v[194:197], v[64:67]
	v_mfma_f32_16x16x32_bf16 v[116:119], v[148:151], v[164:167], v[116:119]
	v_mfma_f32_16x16x32_bf16 v[112:115], v[156:159], v[164:167], v[112:115]
	v_mfma_f32_16x16x32_bf16 v[100:103], v[148:151], v[172:175], v[100:103]
	v_mfma_f32_16x16x32_bf16 v[96:99], v[156:159], v[172:175], v[96:99]
	v_mfma_f32_16x16x32_bf16 v[84:87], v[148:151], v[180:183], v[84:87]
	v_mfma_f32_16x16x32_bf16 v[80:83], v[156:159], v[180:183], v[80:83]
	v_mfma_f32_16x16x32_bf16 v[68:71], v[148:151], v[198:201], v[68:71]
	v_mfma_f32_16x16x32_bf16 v[64:67], v[156:159], v[198:201], v[64:67]
	s_setprio 0
	s_barrier
	s_add_i32 s91, s91, s29
	v_lshl_add_u64 v[202:203], s[24:25], 0, v[204:205]
	s_mov_b32 m0, s91
	ds_read_b128 v[160:163], v235 offset:16384
	ds_read_b128 v[164:167], v235 offset:17408
	ds_read_b128 v[168:171], v235 offset:18432
	ds_read_b128 v[172:175], v235 offset:19456
	ds_read_b128 v[176:179], v235 offset:20480
	ds_read_b128 v[180:183], v235 offset:21504
	ds_read_b128 v[194:197], v235 offset:22528
	ds_read_b128 v[198:201], v235 offset:23552
	global_load_lds_dwordx4 v[202:203], off
	s_add_i32 m0, s91, 0x2000
	s_add_u32 vcc_lo, s24, 0x200000
	v_lshl_add_u64 v[206:207], s[24:25], 0, v[188:189]
	s_addc_u32 vcc_hi, s25, 0
	s_add_i32 s91, s97, s29
	global_load_lds_dwordx4 v[206:207], off
	v_lshl_add_u64 v[208:209], vcc, 0, v[204:205]
	s_mov_b32 m0, s91
	v_lshl_add_u64 v[222:223], s[26:27], 0, v[186:187]
	global_load_lds_dwordx4 v[208:209], off
	v_lshl_add_u64 v[208:209], vcc, 0, v[188:189]
	s_add_i32 m0, s91, 0x2000
	s_nop 0
	global_load_lds_dwordx4 v[208:209], off
	v_lshl_add_u64 v[208:209], s[26:27], 0, v[184:185]
	s_mov_b32 m0, s30
	s_nop 0
	global_load_lds_dwordx4 v[208:209], off
	s_mov_b32 m0, s31
	s_nop 0
	global_load_lds_dwordx4 v[222:223], off
	s_waitcnt vmcnt(8)
	s_waitcnt lgkmcnt(0)
	s_barrier
; #define PG8_STAGE(bufoff, gbase, voff) do { _Pragma("unroll") for (int _i = 0; _i < 2; ++_i) \
;         __builtin_amdgcn_global_load_lds((const unsigned*)((const char*)(gbase) + (voff)[_i]), (LAS unsigned*)(lds + (bufoff) + ldsw + _i * 8192), 16, 0, 0); } while (0)
; #define PG8_LDA(dst, b, h) do { _Pragma("unroll") for (int m = 0; m < 4; ++m) _Pragma("unroll") for (int k = 0; k < 2; ++k) dst[m][k] = *(const LAS bf16x8*)(lds + PG8_SA(b, h) + aoff + m * 2048 + k * 1024); } while (0)
; #define PG8_LDB(dst, b, h) do { _Pragma("unroll") for (int n = 0; n < 2; ++n) _Pragma("unroll") for (int k = 0; k < 2; ++k) dst[n][k] = *(const LAS bf16x8*)(lds + PG8_SB(b, h) + boff + n * 2048 + k * 1024); } while (0)
; #define PG8_MMA(ai, bj, At, Bt) do { __builtin_amdgcn_s_setprio(1); _Pragma("unroll") for (int m = 0; m < 4; ++m) _Pragma("unroll") for (int n = 0; n < 2; ++n) _Pragma("unroll") for (int k = 0; k < 2; ++k) \
;         acc[ai][bj][m][n] = __builtin_amdgcn_mfma_f32_16x16x32_bf16(Bt[n][k], At[m][k], acc[ai][bj][m][n], 0, 0, 0); __builtin_amdgcn_s_setprio(0); } while (0)
; #define PG8_WAIT_V(n) asm volatile("s_waitcnt vmcnt(" #n ")" ::: "memory")
; #define PG8_WAIT_L(n) asm volatile("s_waitcnt lgkmcnt(" #n ")" ::: "memory")
; #define PG8_BAR __builtin_amdgcn_s_barrier()
; #define PG8_SCHED __builtin_amdgcn_sched_barrier(0)
; template <class Epi, class Sched, bool ALIGN_EPI = false, bool SP2 = false>
; DI void gemm_phase(LAS unsigned char* lds, const Gemm g, const Sched& S, const Epi& E, const int tidx) {
;     ...
;             PG8_WAIT_V(8); PG8_WAIT_L(0); PG8_BAR; PG8_MMA(1, 0, At, B0); PG8_MMA(1, 1, At, B1); PG8_BAR; PG8_SCHED;
;             PG8_LDB(B0, 1, 0); PG8_LDB(B1, 1, 1); PG8_SCHED; PG8_LDA(At, 1, 0); PG8_STAGE(PG8_SA(0, 1), a2 + hstepA, voffA);
;             PG8_WAIT_V(8); PG8_WAIT_L(0); PG8_BAR; PG8_MMA(0, 0, At, B0); PG8_MMA(0, 1, At, B1); PG8_BAR; PG8_SCHED;
;             PG8_LDA(At, 1, 1); PG8_STAGE(PG8_SB(1, 0), b3, voffB); PG8_STAGE(PG8_SB(1, 1), b3 + hstepB, voffB); PG8_STAGE(PG8_SA(1, 0), a3, voffA);
	s_setprio 1
	s_waitcnt lgkmcnt(0)
	v_mfma_f32_16x16x32_bf16 v[60:63], v[128:131], v[160:163], v[60:63]
	v_mfma_f32_16x16x32_bf16 v[56:59], v[136:139], v[160:163], v[56:59]
	v_mfma_f32_16x16x32_bf16 v[44:47], v[128:131], v[168:171], v[44:47]
	v_mfma_f32_16x16x32_bf16 v[40:43], v[136:139], v[168:171], v[40:43]
	v_mfma_f32_16x16x32_bf16 v[28:31], v[128:131], v[176:179], v[28:31]
	v_mfma_f32_16x16x32_bf16 v[24:27], v[136:139], v[176:179], v[24:27]
	v_mfma_f32_16x16x32_bf16 v[12:15], v[128:131], v[194:197], v[12:15]
	v_mfma_f32_16x16x32_bf16 v[8:11], v[136:139], v[194:197], v[8:11]
	v_mfma_f32_16x16x32_bf16 v[60:63], v[132:135], v[164:167], v[60:63]
	v_mfma_f32_16x16x32_bf16 v[56:59], v[140:143], v[164:167], v[56:59]
	v_mfma_f32_16x16x32_bf16 v[44:47], v[132:135], v[172:175], v[44:47]
	v_mfma_f32_16x16x32_bf16 v[40:43], v[140:143], v[172:175], v[40:43]
	v_mfma_f32_16x16x32_bf16 v[28:31], v[132:135], v[180:183], v[28:31]
	v_mfma_f32_16x16x32_bf16 v[24:27], v[140:143], v[180:183], v[24:27]
	v_mfma_f32_16x16x32_bf16 v[12:15], v[132:135], v[198:201], v[12:15]
	v_mfma_f32_16x16x32_bf16 v[8:11], v[140:143], v[198:201], v[8:11]
	v_mfma_f32_16x16x32_bf16 v[52:55], v[144:147], v[160:163], v[52:55]
	v_mfma_f32_16x16x32_bf16 v[48:51], v[152:155], v[160:163], v[48:51]
	v_mfma_f32_16x16x32_bf16 v[36:39], v[144:147], v[168:171], v[36:39]
	v_mfma_f32_16x16x32_bf16 v[32:35], v[152:155], v[168:171], v[32:35]
	v_mfma_f32_16x16x32_bf16 v[20:23], v[144:147], v[176:179], v[20:23]
	v_mfma_f32_16x16x32_bf16 v[16:19], v[152:155], v[176:179], v[16:19]
	v_mfma_f32_16x16x32_bf16 v[4:7], v[144:147], v[194:197], v[4:7]
	v_mfma_f32_16x16x32_bf16 v[0:3], v[152:155], v[194:197], v[0:3]
	v_mfma_f32_16x16x32_bf16 v[52:55], v[148:151], v[164:167], v[52:55]
	v_mfma_f32_16x16x32_bf16 v[48:51], v[156:159], v[164:167], v[48:51]
	v_mfma_f32_16x16x32_bf16 v[36:39], v[148:151], v[172:175], v[36:39]
	v_mfma_f32_16x16x32_bf16 v[32:35], v[156:159], v[172:175], v[32:35]
	v_mfma_f32_16x16x32_bf16 v[20:23], v[148:151], v[180:183], v[20:23]
	v_mfma_f32_16x16x32_bf16 v[16:19], v[156:159], v[180:183], v[16:19]
	v_mfma_f32_16x16x32_bf16 v[4:7], v[148:151], v[198:201], v[4:7]
	v_mfma_f32_16x16x32_bf16 v[0:3], v[156:159], v[198:201], v[0:3]
	s_setprio 0
	s_barrier
	s_add_i32 s91, 0, 0x18000
	s_add_i32 s97, 0, 0x1c000
	v_add_u32_e32 v140, s91, v221
	v_add_u32_e32 v156, s97, v221
	ds_read_b128 v[128:131], v140
	ds_read_b128 v[132:135], v140 offset:1024
	ds_read_b128 v[136:139], v140 offset:2048
	ds_read_b128 v[140:143], v140 offset:3072
	ds_read_b128 v[144:147], v156
	ds_read_b128 v[148:151], v156 offset:1024
	ds_read_b128 v[152:155], v156 offset:2048
	ds_read_b128 v[156:159], v156 offset:3072
	s_add_u32 s26, s26, 0x200000
	s_addc_u32 s27, s27, 0
	s_mov_b32 m0, s36
	v_lshl_add_u64 v[224:225], s[26:27], 0, v[184:185]
	ds_read_b128 v[160:163], v235 offset:32768
	ds_read_b128 v[164:167], v235 offset:33792
	ds_read_b128 v[168:171], v235 offset:34816
	ds_read_b128 v[172:175], v235 offset:35840
	ds_read_b128 v[176:179], v235 offset:36864
	ds_read_b128 v[180:183], v235 offset:37888
	ds_read_b128 v[194:197], v235 offset:38912
	ds_read_b128 v[198:201], v235 offset:39936
	global_load_lds_dwordx4 v[224:225], off
	v_lshl_add_u64 v[224:225], s[26:27], 0, v[186:187]
	s_mov_b32 m0, s37
	s_nop 0
	global_load_lds_dwordx4 v[224:225], off
	s_waitcnt vmcnt(8)
	s_waitcnt lgkmcnt(0)
	s_barrier
	s_setprio 1
	s_waitcnt lgkmcnt(0)
	v_mfma_f32_16x16x32_bf16 v[124:127], v[128:131], v[160:163], v[124:127]
	v_mfma_f32_16x16x32_bf16 v[120:123], v[136:139], v[160:163], v[120:123]
	v_mfma_f32_16x16x32_bf16 v[108:111], v[128:131], v[168:171], v[108:111]
	v_mfma_f32_16x16x32_bf16 v[104:107], v[136:139], v[168:171], v[104:107]
	v_mfma_f32_16x16x32_bf16 v[92:95], v[128:131], v[176:179], v[92:95]
	v_mfma_f32_16x16x32_bf16 v[88:91], v[136:139], v[176:179], v[88:91]
	v_mfma_f32_16x16x32_bf16 v[76:79], v[128:131], v[194:197], v[76:79]
	v_mfma_f32_16x16x32_bf16 v[72:75], v[136:139], v[194:197], v[72:75]
	v_mfma_f32_16x16x32_bf16 v[124:127], v[132:135], v[164:167], v[124:127]
	v_mfma_f32_16x16x32_bf16 v[120:123], v[140:143], v[164:167], v[120:123]
	v_mfma_f32_16x16x32_bf16 v[108:111], v[132:135], v[172:175], v[108:111]
	v_mfma_f32_16x16x32_bf16 v[104:107], v[140:143], v[172:175], v[104:107]
	v_mfma_f32_16x16x32_bf16 v[92:95], v[132:135], v[180:183], v[92:95]
	v_mfma_f32_16x16x32_bf16 v[88:91], v[140:143], v[180:183], v[88:91]
	v_mfma_f32_16x16x32_bf16 v[76:79], v[132:135], v[198:201], v[76:79]
	v_mfma_f32_16x16x32_bf16 v[72:75], v[140:143], v[198:201], v[72:75]
	v_mfma_f32_16x16x32_bf16 v[116:119], v[144:147], v[160:163], v[116:119]
	v_mfma_f32_16x16x32_bf16 v[112:115], v[152:155], v[160:163], v[112:115]
	v_mfma_f32_16x16x32_bf16 v[100:103], v[144:147], v[168:171], v[100:103]
	v_mfma_f32_16x16x32_bf16 v[96:99], v[152:155], v[168:171], v[96:99]
	v_mfma_f32_16x16x32_bf16 v[84:87], v[144:147], v[176:179], v[84:87]
	v_mfma_f32_16x16x32_bf16 v[80:83], v[152:155], v[176:179], v[80:83]
	v_mfma_f32_16x16x32_bf16 v[68:71], v[144:147], v[194:197], v[68:71]
	v_mfma_f32_16x16x32_bf16 v[64:67], v[152:155], v[194:197], v[64:67]
	v_mfma_f32_16x16x32_bf16 v[116:119], v[148:151], v[164:167], v[116:119]
	v_mfma_f32_16x16x32_bf16 v[112:115], v[156:159], v[164:167], v[112:115]
	v_mfma_f32_16x16x32_bf16 v[100:103], v[148:151], v[172:175], v[100:103]
	v_mfma_f32_16x16x32_bf16 v[96:99], v[156:159], v[172:175], v[96:99]
	v_mfma_f32_16x16x32_bf16 v[84:87], v[148:151], v[180:183], v[84:87]
	v_mfma_f32_16x16x32_bf16 v[80:83], v[156:159], v[180:183], v[80:83]
	v_mfma_f32_16x16x32_bf16 v[68:71], v[148:151], v[198:201], v[68:71]
	v_mfma_f32_16x16x32_bf16 v[64:67], v[156:159], v[198:201], v[64:67]
	s_setprio 0
	s_barrier
; #define PG8_STAGE(bufoff, gbase, voff) do { _Pragma("unroll") for (int _i = 0; _i < 2; ++_i) \
;         __builtin_amdgcn_global_load_lds((const unsigned*)((const char*)(gbase) + (voff)[_i]), (LAS unsigned*)(lds + (bufoff) + ldsw + _i * 8192), 16, 0, 0); } while (0)
; #define PG8_LDA(dst, b, h) do { _Pragma("unroll") for (int m = 0; m < 4; ++m) _Pragma("unroll") for (int k = 0; k < 2; ++k) dst[m][k] = *(const LAS bf16x8*)(lds + PG8_SA(b, h) + aoff + m * 2048 + k * 1024); } while (0)
; #define PG8_MMA(ai, bj, At, Bt) do { __builtin_amdgcn_s_setprio(1); _Pragma("unroll") for (int m = 0; m < 4; ++m) _Pragma("unroll") for (int n = 0; n < 2; ++n) _Pragma("unroll") for (int k = 0; k < 2; ++k) \
;         acc[ai][bj][m][n] = __builtin_amdgcn_mfma_f32_16x16x32_bf16(Bt[n][k], At[m][k], acc[ai][bj][m][n], 0, 0, 0); __builtin_amdgcn_s_setprio(0); } while (0)
; #define PG8_WAIT_V(n) asm volatile("s_waitcnt vmcnt(" #n ")" ::: "memory")
; #define PG8_WAIT_L(n) asm volatile("s_waitcnt lgkmcnt(" #n ")" ::: "memory")
; #define PG8_BAR __builtin_amdgcn_s_barrier()
; #define PG8_SCHED __builtin_amdgcn_sched_barrier(0)
;     DI void operator()(const f32x4 (&acc)[2][2][4][2], const Unit& u, int wr, int wc, int fr, int fq) const {
;         const int row0 = u.pm * BM + wr * 64 + fr, col0 = u.pn * BM + wc * 32 + 8 * fq;
;         f32x4 qa[2][2][2], qb[2][2][2];
; template <class Epi, class Sched, bool ALIGN_EPI = false, bool SP2 = false>
; DI void gemm_phase(LAS unsigned char* lds, const Gemm g, const Sched& S, const Epi& E, const int tidx) {
;     ...
;             PG8_LDA(At, 1, 1); PG8_STAGE(PG8_SB(1, 0), b3, voffB); PG8_STAGE(PG8_SB(1, 1), b3 + hstepB, voffB); PG8_STAGE(PG8_SA(1, 0), a3, voffA);
;             PG8_WAIT_V(8); PG8_WAIT_L(0); PG8_BAR; PG8_MMA(1, 0, At, B0); PG8_MMA(1, 1, At, B1); PG8_BAR; PG8_SCHED;
	s_add_i32 s26, s91, s29
	v_lshl_add_u64 v[202:203], v[202:203], 0, s[92:93]
	s_mov_b32 m0, s26
	ds_read_b128 v[160:163], v235 offset:49152
	ds_read_b128 v[164:167], v235 offset:50176
	ds_read_b128 v[168:171], v235 offset:51200
	ds_read_b128 v[172:175], v235 offset:52224
	ds_read_b128 v[176:179], v235 offset:53248
	ds_read_b128 v[180:183], v235 offset:54272
	ds_read_b128 v[194:197], v235 offset:55296
	ds_read_b128 v[198:201], v235 offset:56320
	global_load_lds_dwordx4 v[202:203], off
	s_add_i32 m0, s26, 0x2000
	s_add_u32 s24, s24, 0x200080
	v_lshl_add_u64 v[202:203], v[206:207], 0, s[92:93]
	s_addc_u32 s25, s25, 0
	s_add_i32 s26, s97, s29
	global_load_lds_dwordx4 v[202:203], off
	v_lshl_add_u64 v[202:203], s[24:25], 0, v[204:205]
	s_mov_b32 m0, s26
	s_nop 0
	global_load_lds_dwordx4 v[202:203], off
	v_lshl_add_u64 v[202:203], s[24:25], 0, v[188:189]
	s_add_i32 m0, s26, 0x2000
	s_nop 0
	global_load_lds_dwordx4 v[202:203], off
	v_lshl_add_u64 v[202:203], v[208:209], 0, s[92:93]
	s_mov_b32 m0, s51
	s_nop 0
	global_load_lds_dwordx4 v[202:203], off
	v_lshl_add_u64 v[202:203], v[222:223], 0, s[92:93]
	s_mov_b32 m0, s54
	s_nop 0
	global_load_lds_dwordx4 v[202:203], off
	s_waitcnt vmcnt(8)
	s_waitcnt lgkmcnt(0)
	s_barrier
	s_setprio 1
	s_waitcnt lgkmcnt(0)
	v_mfma_f32_16x16x32_bf16 v[60:63], v[128:131], v[160:163], v[60:63]
	v_mfma_f32_16x16x32_bf16 v[56:59], v[136:139], v[160:163], v[56:59]
	v_mfma_f32_16x16x32_bf16 v[44:47], v[128:131], v[168:171], v[44:47]
	v_mfma_f32_16x16x32_bf16 v[40:43], v[136:139], v[168:171], v[40:43]
	v_mfma_f32_16x16x32_bf16 v[28:31], v[128:131], v[176:179], v[28:31]
	v_mfma_f32_16x16x32_bf16 v[24:27], v[136:139], v[176:179], v[24:27]
	v_mfma_f32_16x16x32_bf16 v[12:15], v[128:131], v[194:197], v[12:15]
	v_mfma_f32_16x16x32_bf16 v[8:11], v[136:139], v[194:197], v[8:11]
	v_mfma_f32_16x16x32_bf16 v[60:63], v[132:135], v[164:167], v[60:63]
	v_mfma_f32_16x16x32_bf16 v[56:59], v[140:143], v[164:167], v[56:59]
	v_mfma_f32_16x16x32_bf16 v[44:47], v[132:135], v[172:175], v[44:47]
	v_mfma_f32_16x16x32_bf16 v[40:43], v[140:143], v[172:175], v[40:43]
	v_mfma_f32_16x16x32_bf16 v[28:31], v[132:135], v[180:183], v[28:31]
	v_mfma_f32_16x16x32_bf16 v[24:27], v[140:143], v[180:183], v[24:27]
	v_mfma_f32_16x16x32_bf16 v[12:15], v[132:135], v[198:201], v[12:15]
	v_mfma_f32_16x16x32_bf16 v[8:11], v[140:143], v[198:201], v[8:11]
	v_mfma_f32_16x16x32_bf16 v[52:55], v[144:147], v[160:163], v[52:55]
	v_mfma_f32_16x16x32_bf16 v[48:51], v[152:155], v[160:163], v[48:51]
	v_mfma_f32_16x16x32_bf16 v[36:39], v[144:147], v[168:171], v[36:39]
	v_mfma_f32_16x16x32_bf16 v[32:35], v[152:155], v[168:171], v[32:35]
	v_mfma_f32_16x16x32_bf16 v[20:23], v[144:147], v[176:179], v[20:23]
	v_mfma_f32_16x16x32_bf16 v[16:19], v[152:155], v[176:179], v[16:19]
	v_mfma_f32_16x16x32_bf16 v[4:7], v[144:147], v[194:197], v[4:7]
	v_mfma_f32_16x16x32_bf16 v[0:3], v[152:155], v[194:197], v[0:3]
	v_mfma_f32_16x16x32_bf16 v[52:55], v[148:151], v[164:167], v[52:55]
	v_mfma_f32_16x16x32_bf16 v[48:51], v[156:159], v[164:167], v[48:51]
	v_mfma_f32_16x16x32_bf16 v[36:39], v[148:151], v[172:175], v[36:39]
	v_mfma_f32_16x16x32_bf16 v[32:35], v[156:159], v[172:175], v[32:35]
	v_mfma_f32_16x16x32_bf16 v[20:23], v[148:151], v[180:183], v[20:23]
	v_mfma_f32_16x16x32_bf16 v[16:19], v[156:159], v[180:183], v[16:19]
	v_mfma_f32_16x16x32_bf16 v[4:7], v[148:151], v[198:201], v[4:7]
	v_mfma_f32_16x16x32_bf16 v[0:3], v[156:159], v[198:201], v[0:3]
	s_setprio 0
	s_barrier
	s_add_i32 s83, s83, 2
	s_add_u32 s57, s57, 0x100
	s_addc_u32 s82, s82, 0
	s_add_u32 s22, s22, 0x100
	s_addc_u32 s23, s23, 0
	s_cmpk_gt_u32 s83, 0x7d
	s_cbranch_scc0 .LBB0_39
	v_lshl_add_u32 v198, s4, 8, v215
	v_lshl_or_b32 v194, s20, 8, v234
	v_ashrrev_i32_e32 v195, 31, v194
	v_ashrrev_i32_e32 v199, 31, v198
	v_or_b32_e32 v226, 16, v198
	v_lshl_add_u64 v[196:197], v[194:195], 2, s[8:9]
	v_lshlrev_b64 v[128:129], 13, v[198:199]
	v_ashrrev_i32_e32 v227, 31, v226
	v_or_b32_e32 v222, 32, v198
	v_lshl_add_u64 v[230:231], v[196:197], 0, v[128:129]
	v_lshlrev_b64 v[128:129], 13, v[226:227]
	v_ashrrev_i32_e32 v223, 31, v222
	v_or_b32_e32 v200, 48, v198
	v_lshl_add_u64 v[228:229], v[196:197], 0, v[128:129]
	v_lshlrev_b64 v[128:129], 13, v[222:223]
	v_ashrrev_i32_e32 v201, 31, v200
	v_lshl_add_u64 v[224:225], v[196:197], 0, v[128:129]
	v_lshlrev_b64 v[128:129], 13, v[200:201]
	v_lshl_add_u64 v[202:203], v[196:197], 0, v[128:129]
	global_load_dwordx4 v[248:251], v[230:231], off offset:16
	global_load_dwordx4 v[206:209], v[230:231], off
	global_load_dwordx4 v[176:179], v[230:231], off offset:528
	global_load_dwordx4 v[180:183], v[230:231], off offset:512
	global_load_dwordx4 v[168:171], v[228:229], off offset:16
	global_load_dwordx4 v[172:175], v[228:229], off
	global_load_dwordx4 v[160:163], v[228:229], off offset:528
	global_load_dwordx4 v[164:167], v[228:229], off offset:512
	global_load_dwordx4 v[152:155], v[224:225], off offset:16
	global_load_dwordx4 v[156:159], v[224:225], off
	global_load_dwordx4 v[144:147], v[224:225], off offset:528
	global_load_dwordx4 v[148:151], v[224:225], off offset:512
	global_load_dwordx4 v[136:139], v[202:203], off offset:16
	global_load_dwordx4 v[140:143], v[202:203], off
	global_load_dwordx4 v[128:131], v[202:203], off offset:528
	global_load_dwordx4 v[132:135], v[202:203], off offset:512
	v_lshlrev_b64 v[232:233], 11, v[198:199]
	v_lshl_add_u64 v[232:233], v[232:233], 0, v[194:195]
	s_waitcnt vmcnt(0)
	v_pk_add_f32 v[124:125], v[124:125], v[206:207]
	v_cndmask_b32_e64 v206, 0, 1, s[10:11]
	v_pk_add_f32 v[126:127], v[126:127], v[208:209]
	v_pk_add_f32 v[122:123], v[122:123], v[250:251]
	v_pk_add_f32 v[120:121], v[120:121], v[248:249]
	v_cmp_ne_u32_e64 s[4:5], 1, v206
	s_andn2_b64 vcc, exec, s[10:11]
	v_lshl_add_u64 v[232:233], v[232:233], 1, s[78:79]
	global_store_dwordx4 v[230:231], v[124:127], off
	global_store_dwordx4 v[230:231], v[120:123], off offset:16
	s_cbranch_vccnz .LBB0_42
	v_cvt_pk_bf16_f32 v206, v124, v125
	v_cvt_pk_bf16_f32 v207, v126, v127
	v_cvt_pk_bf16_f32 v208, v120, v121
	v_cvt_pk_bf16_f32 v209, v122, v123
	global_store_dwordx4 v[232:233], v[206:209], off

; #define PG8_STAGE(bufoff, gbase, voff) do { _Pragma("unroll") for (int _i = 0; _i < 2; ++_i) \
;         __builtin_amdgcn_global_load_lds((const unsigned*)((const char*)(gbase) + (voff)[_i]), (LAS unsigned*)(lds + (bufoff) + ldsw + _i * 8192), 16, 0, 0); } while (0)
; #define PG8_LDA(dst, b, h) do { _Pragma("unroll") for (int m = 0; m < 4; ++m) _Pragma("unroll") for (int k = 0; k < 2; ++k) dst[m][k] = *(const LAS bf16x8*)(lds + PG8_SA(b, h) + aoff + m * 2048 + k * 1024); } while (0)
; #define PG8_LDB(dst, b, h) do { _Pragma("unroll") for (int n = 0; n < 2; ++n) _Pragma("unroll") for (int k = 0; k < 2; ++k) dst[n][k] = *(const LAS bf16x8*)(lds + PG8_SB(b, h) + boff + n * 2048 + k * 1024); } while (0)
; #define PG8_MMA(ai, bj, At, Bt) do { __builtin_amdgcn_s_setprio(1); _Pragma("unroll") for (int m = 0; m < 4; ++m) _Pragma("unroll") for (int n = 0; n < 2; ++n) _Pragma("unroll") for (int k = 0; k < 2; ++k) \
;         acc[ai][bj][m][n] = __builtin_amdgcn_mfma_f32_16x16x32_bf16(Bt[n][k], At[m][k], acc[ai][bj][m][n], 0, 0, 0); __builtin_amdgcn_s_setprio(0); } while (0)
; #define PG8_WAIT_V(n) asm volatile("s_waitcnt vmcnt(" #n ")" ::: "memory")
; #define PG8_WAIT_L(n) asm volatile("s_waitcnt lgkmcnt(" #n ")" ::: "memory")
; #define PG8_BAR __builtin_amdgcn_s_barrier()
; #define PG8_SCHED __builtin_amdgcn_sched_barrier(0)
; template <class Epi, class Sched, bool ALIGN_EPI = false, bool SP2 = false>
; DI void gemm_phase(LAS unsigned char* lds, const Gemm g, const Sched& S, const Epi& E, const int tidx) {
;     ...
;             PG8_LDB(B0, 0, 0); PG8_LDB(B1, 0, 1); PG8_SCHED; PG8_LDA(At, 0, 0); PG8_STAGE(PG8_SA(1, 1), a1 + hstepA, voffA);
;             PG8_WAIT_V(8); PG8_WAIT_L(0); PG8_BAR; PG8_MMA(0, 0, At, B0); PG8_MMA(0, 1, At, B1); PG8_BAR; PG8_SCHED;
;             PG8_LDA(At, 0, 1); PG8_STAGE(PG8_SB(0, 0), b2, voffB); PG8_STAGE(PG8_SB(0, 1), b2 + hstepB, voffB); PG8_STAGE(PG8_SA(0, 0), a2, voffA);
.LBB0_112:
	s_add_u32 s11, s26, 0xffe00080
	s_addc_u32 s28, s27, -1
	s_add_i32 s56, 0, 0x10000
	s_cmpk_eq_i32 s10, 0x7c
	s_cselect_b32 s31, s15, s28
	s_cselect_b32 s30, s23, s11
	s_cselect_b32 s29, s17, vcc_hi
	s_cselect_b32 s28, s25, vcc_lo
	s_add_i32 s11, 0, 0x14000
	v_add_u32_e32 v140, s56, v187
	v_add_u32_e32 v166, s11, v187
	ds_read_b128 v[128:131], v140
	ds_read_b128 v[132:135], v140 offset:1024
	ds_read_b128 v[136:139], v140 offset:2048
	ds_read_b128 v[140:143], v140 offset:3072
	ds_read_b128 v[154:157], v166
	ds_read_b128 v[158:161], v166 offset:1024
	ds_read_b128 v[162:165], v166 offset:2048
	ds_read_b128 v[166:169], v166 offset:3072
	v_lshl_add_u64 v[202:203], s[26:27], 0, v[150:151]
	s_add_i32 m0, s37, 0xc000
	ds_read_b128 v[170:173], v189
	ds_read_b128 v[174:177], v189 offset:1024
	ds_read_b128 v[178:181], v189 offset:2048
	ds_read_b128 v[182:185], v189 offset:3072
	ds_read_b128 v[190:193], v189 offset:4096
	ds_read_b128 v[194:197], v189 offset:5120
	ds_read_b128 v[198:201], v189 offset:6144
	ds_read_b128 v[222:225], v189 offset:7168
	global_load_lds_dwordx4 v[202:203], off
	v_lshl_add_u64 v[202:203], s[26:27], 0, v[152:153]
	s_add_i32 m0, s37, 0xe000
	s_nop 0
	global_load_lds_dwordx4 v[202:203], off
	s_waitcnt vmcnt(8)
	s_waitcnt lgkmcnt(0)
	s_barrier
	s_setprio 1
	s_waitcnt lgkmcnt(0)
	v_mfma_f32_16x16x32_bf16 v[124:127], v[128:131], v[170:173], v[124:127]
	v_mfma_f32_16x16x32_bf16 v[120:123], v[136:139], v[170:173], v[120:123]
	v_mfma_f32_16x16x32_bf16 v[108:111], v[128:131], v[178:181], v[108:111]
	v_mfma_f32_16x16x32_bf16 v[104:107], v[136:139], v[178:181], v[104:107]
	v_mfma_f32_16x16x32_bf16 v[92:95], v[128:131], v[190:193], v[92:95]
	v_mfma_f32_16x16x32_bf16 v[88:91], v[136:139], v[190:193], v[88:91]
	v_mfma_f32_16x16x32_bf16 v[76:79], v[128:131], v[198:201], v[76:79]
	v_mfma_f32_16x16x32_bf16 v[72:75], v[136:139], v[198:201], v[72:75]
	v_mfma_f32_16x16x32_bf16 v[124:127], v[132:135], v[174:177], v[124:127]
	v_mfma_f32_16x16x32_bf16 v[120:123], v[140:143], v[174:177], v[120:123]
	v_mfma_f32_16x16x32_bf16 v[108:111], v[132:135], v[182:185], v[108:111]
	v_mfma_f32_16x16x32_bf16 v[104:107], v[140:143], v[182:185], v[104:107]
	v_mfma_f32_16x16x32_bf16 v[92:95], v[132:135], v[194:197], v[92:95]
	v_mfma_f32_16x16x32_bf16 v[88:91], v[140:143], v[194:197], v[88:91]
	v_mfma_f32_16x16x32_bf16 v[76:79], v[132:135], v[222:225], v[76:79]
	v_mfma_f32_16x16x32_bf16 v[72:75], v[140:143], v[222:225], v[72:75]
	v_mfma_f32_16x16x32_bf16 v[116:119], v[154:157], v[170:173], v[116:119]
	v_mfma_f32_16x16x32_bf16 v[112:115], v[162:165], v[170:173], v[112:115]
	v_mfma_f32_16x16x32_bf16 v[100:103], v[154:157], v[178:181], v[100:103]
	v_mfma_f32_16x16x32_bf16 v[96:99], v[162:165], v[178:181], v[96:99]
	v_mfma_f32_16x16x32_bf16 v[84:87], v[154:157], v[190:193], v[84:87]
	v_mfma_f32_16x16x32_bf16 v[80:83], v[162:165], v[190:193], v[80:83]
	v_mfma_f32_16x16x32_bf16 v[68:71], v[154:157], v[198:201], v[68:71]
	v_mfma_f32_16x16x32_bf16 v[64:67], v[162:165], v[198:201], v[64:67]
	v_mfma_f32_16x16x32_bf16 v[116:119], v[158:161], v[174:177], v[116:119]
	v_mfma_f32_16x16x32_bf16 v[112:115], v[166:169], v[174:177], v[112:115]
	v_mfma_f32_16x16x32_bf16 v[100:103], v[158:161], v[182:185], v[100:103]
	v_mfma_f32_16x16x32_bf16 v[96:99], v[166:169], v[182:185], v[96:99]
	v_mfma_f32_16x16x32_bf16 v[84:87], v[158:161], v[194:197], v[84:87]
	v_mfma_f32_16x16x32_bf16 v[80:83], v[166:169], v[194:197], v[80:83]
	v_mfma_f32_16x16x32_bf16 v[68:71], v[158:161], v[222:225], v[68:71]
	v_mfma_f32_16x16x32_bf16 v[64:67], v[166:169], v[222:225], v[64:67]
	s_setprio 0
	s_barrier
	s_add_i32 s56, s56, s36
	v_lshl_add_u64 v[202:203], s[28:29], 0, v[204:205]
	s_mov_b32 m0, s56
	ds_read_b128 v[170:173], v189 offset:16384
	ds_read_b128 v[174:177], v189 offset:17408
	ds_read_b128 v[178:181], v189 offset:18432
	ds_read_b128 v[182:185], v189 offset:19456
	ds_read_b128 v[190:193], v189 offset:20480
	ds_read_b128 v[194:197], v189 offset:21504
	ds_read_b128 v[198:201], v189 offset:22528
	ds_read_b128 v[222:225], v189 offset:23552
	global_load_lds_dwordx4 v[202:203], off
	s_add_i32 m0, s56, 0x2000
	s_add_u32 s56, s28, 0x200000
	v_lshl_add_u64 v[206:207], s[28:29], 0, v[148:149]
	s_addc_u32 s57, s29, 0
	s_add_i32 s11, s11, s36
	global_load_lds_dwordx4 v[206:207], off
	v_lshl_add_u64 v[208:209], s[56:57], 0, v[204:205]
	s_mov_b32 m0, s11
	v_lshl_add_u64 v[226:227], s[30:31], 0, v[146:147]
	global_load_lds_dwordx4 v[208:209], off
	v_lshl_add_u64 v[208:209], s[56:57], 0, v[148:149]
	s_add_i32 m0, s11, 0x2000
	s_nop 0
	global_load_lds_dwordx4 v[208:209], off
	v_lshl_add_u64 v[208:209], s[30:31], 0, v[144:145]
	s_mov_b32 m0, s37
	s_nop 0
	global_load_lds_dwordx4 v[208:209], off
	s_mov_b32 m0, s51
	s_nop 0
	global_load_lds_dwordx4 v[226:227], off
	s_waitcnt vmcnt(8)
	s_waitcnt lgkmcnt(0)
	s_barrier
; #define PG8_STAGE(bufoff, gbase, voff) do { _Pragma("unroll") for (int _i = 0; _i < 2; ++_i) \
;         __builtin_amdgcn_global_load_lds((const unsigned*)((const char*)(gbase) + (voff)[_i]), (LAS unsigned*)(lds + (bufoff) + ldsw + _i * 8192), 16, 0, 0); } while (0)
; #define PG8_LDA(dst, b, h) do { _Pragma("unroll") for (int m = 0; m < 4; ++m) _Pragma("unroll") for (int k = 0; k < 2; ++k) dst[m][k] = *(const LAS bf16x8*)(lds + PG8_SA(b, h) + aoff + m * 2048 + k * 1024); } while (0)
; #define PG8_LDB(dst, b, h) do { _Pragma("unroll") for (int n = 0; n < 2; ++n) _Pragma("unroll") for (int k = 0; k < 2; ++k) dst[n][k] = *(const LAS bf16x8*)(lds + PG8_SB(b, h) + boff + n * 2048 + k * 1024); } while (0)
; #define PG8_MMA(ai, bj, At, Bt) do { __builtin_amdgcn_s_setprio(1); _Pragma("unroll") for (int m = 0; m < 4; ++m) _Pragma("unroll") for (int n = 0; n < 2; ++n) _Pragma("unroll") for (int k = 0; k < 2; ++k) \
;         acc[ai][bj][m][n] = __builtin_amdgcn_mfma_f32_16x16x32_bf16(Bt[n][k], At[m][k], acc[ai][bj][m][n], 0, 0, 0); __builtin_amdgcn_s_setprio(0); } while (0)
; #define PG8_WAIT_V(n) asm volatile("s_waitcnt vmcnt(" #n ")" ::: "memory")
; #define PG8_WAIT_L(n) asm volatile("s_waitcnt lgkmcnt(" #n ")" ::: "memory")
; #define PG8_BAR __builtin_amdgcn_s_barrier()
; #define PG8_SCHED __builtin_amdgcn_sched_barrier(0)
; template <class Epi, class Sched, bool ALIGN_EPI = false, bool SP2 = false>
; DI void gemm_phase(LAS unsigned char* lds, const Gemm g, const Sched& S, const Epi& E, const int tidx) {
;     ...
;             PG8_WAIT_V(8); PG8_WAIT_L(0); PG8_BAR; PG8_MMA(1, 0, At, B0); PG8_MMA(1, 1, At, B1); PG8_BAR; PG8_SCHED;
;             PG8_LDB(B0, 1, 0); PG8_LDB(B1, 1, 1); PG8_SCHED; PG8_LDA(At, 1, 0); PG8_STAGE(PG8_SA(0, 1), a2 + hstepA, voffA);
;             PG8_WAIT_V(8); PG8_WAIT_L(0); PG8_BAR; PG8_MMA(0, 0, At, B0); PG8_MMA(0, 1, At, B1); PG8_BAR; PG8_SCHED;
;             PG8_LDA(At, 1, 1); PG8_STAGE(PG8_SB(1, 0), b3, voffB); PG8_STAGE(PG8_SB(1, 1), b3 + hstepB, voffB); PG8_STAGE(PG8_SA(1, 0), a3, voffA);
	s_setprio 1
	s_waitcnt lgkmcnt(0)
	v_mfma_f32_16x16x32_bf16 v[60:63], v[128:131], v[170:173], v[60:63]
	v_mfma_f32_16x16x32_bf16 v[56:59], v[136:139], v[170:173], v[56:59]
	v_mfma_f32_16x16x32_bf16 v[44:47], v[128:131], v[178:181], v[44:47]
	v_mfma_f32_16x16x32_bf16 v[40:43], v[136:139], v[178:181], v[40:43]
	v_mfma_f32_16x16x32_bf16 v[28:31], v[128:131], v[190:193], v[28:31]
	v_mfma_f32_16x16x32_bf16 v[24:27], v[136:139], v[190:193], v[24:27]
	v_mfma_f32_16x16x32_bf16 v[12:15], v[128:131], v[198:201], v[12:15]
	v_mfma_f32_16x16x32_bf16 v[8:11], v[136:139], v[198:201], v[8:11]
	v_mfma_f32_16x16x32_bf16 v[60:63], v[132:135], v[174:177], v[60:63]
	v_mfma_f32_16x16x32_bf16 v[56:59], v[140:143], v[174:177], v[56:59]
	v_mfma_f32_16x16x32_bf16 v[44:47], v[132:135], v[182:185], v[44:47]
	v_mfma_f32_16x16x32_bf16 v[40:43], v[140:143], v[182:185], v[40:43]
	v_mfma_f32_16x16x32_bf16 v[28:31], v[132:135], v[194:197], v[28:31]
	v_mfma_f32_16x16x32_bf16 v[24:27], v[140:143], v[194:197], v[24:27]
	v_mfma_f32_16x16x32_bf16 v[12:15], v[132:135], v[222:225], v[12:15]
	v_mfma_f32_16x16x32_bf16 v[8:11], v[140:143], v[222:225], v[8:11]
	v_mfma_f32_16x16x32_bf16 v[52:55], v[154:157], v[170:173], v[52:55]
	v_mfma_f32_16x16x32_bf16 v[48:51], v[162:165], v[170:173], v[48:51]
	v_mfma_f32_16x16x32_bf16 v[36:39], v[154:157], v[178:181], v[36:39]
	v_mfma_f32_16x16x32_bf16 v[32:35], v[162:165], v[178:181], v[32:35]
	v_mfma_f32_16x16x32_bf16 v[20:23], v[154:157], v[190:193], v[20:23]
	v_mfma_f32_16x16x32_bf16 v[16:19], v[162:165], v[190:193], v[16:19]
	v_mfma_f32_16x16x32_bf16 v[4:7], v[154:157], v[198:201], v[4:7]
	v_mfma_f32_16x16x32_bf16 v[0:3], v[162:165], v[198:201], v[0:3]
	v_mfma_f32_16x16x32_bf16 v[52:55], v[158:161], v[174:177], v[52:55]
	v_mfma_f32_16x16x32_bf16 v[48:51], v[166:169], v[174:177], v[48:51]
	v_mfma_f32_16x16x32_bf16 v[36:39], v[158:161], v[182:185], v[36:39]
	v_mfma_f32_16x16x32_bf16 v[32:35], v[166:169], v[182:185], v[32:35]
	v_mfma_f32_16x16x32_bf16 v[20:23], v[158:161], v[194:197], v[20:23]
	v_mfma_f32_16x16x32_bf16 v[16:19], v[166:169], v[194:197], v[16:19]
	v_mfma_f32_16x16x32_bf16 v[4:7], v[158:161], v[222:225], v[4:7]
	v_mfma_f32_16x16x32_bf16 v[0:3], v[166:169], v[222:225], v[0:3]
	s_setprio 0
	s_barrier
	s_add_i32 s11, 0, 0x18000
	s_add_i32 s56, 0, 0x1c000
	v_add_u32_e32 v140, s11, v187
	v_add_u32_e32 v166, s56, v187
	ds_read_b128 v[128:131], v140
	ds_read_b128 v[132:135], v140 offset:1024
	ds_read_b128 v[136:139], v140 offset:2048
	ds_read_b128 v[140:143], v140 offset:3072
	ds_read_b128 v[154:157], v166
	ds_read_b128 v[158:161], v166 offset:1024
	ds_read_b128 v[162:165], v166 offset:2048
	ds_read_b128 v[166:169], v166 offset:3072
	s_add_u32 s30, s30, 0x200000
	s_addc_u32 s31, s31, 0
	s_mov_b32 m0, s54
	v_lshl_add_u64 v[228:229], s[30:31], 0, v[144:145]
	ds_read_b128 v[170:173], v189 offset:32768
	ds_read_b128 v[174:177], v189 offset:33792
	ds_read_b128 v[178:181], v189 offset:34816
	ds_read_b128 v[182:185], v189 offset:35840
	ds_read_b128 v[190:193], v189 offset:36864
	ds_read_b128 v[194:197], v189 offset:37888
	ds_read_b128 v[198:201], v189 offset:38912
	ds_read_b128 v[222:225], v189 offset:39936
	global_load_lds_dwordx4 v[228:229], off
	v_lshl_add_u64 v[228:229], s[30:31], 0, v[146:147]
	s_mov_b32 m0, s55
	s_nop 0
	global_load_lds_dwordx4 v[228:229], off
	s_waitcnt vmcnt(8)
	s_waitcnt lgkmcnt(0)
	s_barrier
	s_setprio 1
	s_waitcnt lgkmcnt(0)
	v_mfma_f32_16x16x32_bf16 v[124:127], v[128:131], v[170:173], v[124:127]
	v_mfma_f32_16x16x32_bf16 v[120:123], v[136:139], v[170:173], v[120:123]
	v_mfma_f32_16x16x32_bf16 v[108:111], v[128:131], v[178:181], v[108:111]
	v_mfma_f32_16x16x32_bf16 v[104:107], v[136:139], v[178:181], v[104:107]
	v_mfma_f32_16x16x32_bf16 v[92:95], v[128:131], v[190:193], v[92:95]
	v_mfma_f32_16x16x32_bf16 v[88:91], v[136:139], v[190:193], v[88:91]
	v_mfma_f32_16x16x32_bf16 v[76:79], v[128:131], v[198:201], v[76:79]
	v_mfma_f32_16x16x32_bf16 v[72:75], v[136:139], v[198:201], v[72:75]
	v_mfma_f32_16x16x32_bf16 v[124:127], v[132:135], v[174:177], v[124:127]
	v_mfma_f32_16x16x32_bf16 v[120:123], v[140:143], v[174:177], v[120:123]
	v_mfma_f32_16x16x32_bf16 v[108:111], v[132:135], v[182:185], v[108:111]
	v_mfma_f32_16x16x32_bf16 v[104:107], v[140:143], v[182:185], v[104:107]
	v_mfma_f32_16x16x32_bf16 v[92:95], v[132:135], v[194:197], v[92:95]
	v_mfma_f32_16x16x32_bf16 v[88:91], v[140:143], v[194:197], v[88:91]
	v_mfma_f32_16x16x32_bf16 v[76:79], v[132:135], v[222:225], v[76:79]
	v_mfma_f32_16x16x32_bf16 v[72:75], v[140:143], v[222:225], v[72:75]
	v_mfma_f32_16x16x32_bf16 v[116:119], v[154:157], v[170:173], v[116:119]
	v_mfma_f32_16x16x32_bf16 v[112:115], v[162:165], v[170:173], v[112:115]
	v_mfma_f32_16x16x32_bf16 v[100:103], v[154:157], v[178:181], v[100:103]
	v_mfma_f32_16x16x32_bf16 v[96:99], v[162:165], v[178:181], v[96:99]
	v_mfma_f32_16x16x32_bf16 v[84:87], v[154:157], v[190:193], v[84:87]
	v_mfma_f32_16x16x32_bf16 v[80:83], v[162:165], v[190:193], v[80:83]
	v_mfma_f32_16x16x32_bf16 v[68:71], v[154:157], v[198:201], v[68:71]
	v_mfma_f32_16x16x32_bf16 v[64:67], v[162:165], v[198:201], v[64:67]
	v_mfma_f32_16x16x32_bf16 v[116:119], v[158:161], v[174:177], v[116:119]
	v_mfma_f32_16x16x32_bf16 v[112:115], v[166:169], v[174:177], v[112:115]
	v_mfma_f32_16x16x32_bf16 v[100:103], v[158:161], v[182:185], v[100:103]
	v_mfma_f32_16x16x32_bf16 v[96:99], v[166:169], v[182:185], v[96:99]
	v_mfma_f32_16x16x32_bf16 v[84:87], v[158:161], v[194:197], v[84:87]
	v_mfma_f32_16x16x32_bf16 v[80:83], v[166:169], v[194:197], v[80:83]
	v_mfma_f32_16x16x32_bf16 v[68:71], v[158:161], v[222:225], v[68:71]
	v_mfma_f32_16x16x32_bf16 v[64:67], v[166:169], v[222:225], v[64:67]
	s_setprio 0
	s_barrier
; #define PG8_STAGE(bufoff, gbase, voff) do { _Pragma("unroll") for (int _i = 0; _i < 2; ++_i) \
;         __builtin_amdgcn_global_load_lds((const unsigned*)((const char*)(gbase) + (voff)[_i]), (LAS unsigned*)(lds + (bufoff) + ldsw + _i * 8192), 16, 0, 0); } while (0)
; #define PG8_LDA(dst, b, h) do { _Pragma("unroll") for (int m = 0; m < 4; ++m) _Pragma("unroll") for (int k = 0; k < 2; ++k) dst[m][k] = *(const LAS bf16x8*)(lds + PG8_SA(b, h) + aoff + m * 2048 + k * 1024); } while (0)
; #define PG8_MMA(ai, bj, At, Bt) do { __builtin_amdgcn_s_setprio(1); _Pragma("unroll") for (int m = 0; m < 4; ++m) _Pragma("unroll") for (int n = 0; n < 2; ++n) _Pragma("unroll") for (int k = 0; k < 2; ++k) \
;         acc[ai][bj][m][n] = __builtin_amdgcn_mfma_f32_16x16x32_bf16(Bt[n][k], At[m][k], acc[ai][bj][m][n], 0, 0, 0); __builtin_amdgcn_s_setprio(0); } while (0)
; #define PG8_WAIT_V(n) asm volatile("s_waitcnt vmcnt(" #n ")" ::: "memory")
; #define PG8_WAIT_L(n) asm volatile("s_waitcnt lgkmcnt(" #n ")" ::: "memory")
; #define PG8_BAR __builtin_amdgcn_s_barrier()
; #define PG8_SCHED __builtin_amdgcn_sched_barrier(0)
; template <class Epi, class Sched, bool ALIGN_EPI = false, bool SP2 = false>
; DI void gemm_phase(LAS unsigned char* lds, const Gemm g, const Sched& S, const Epi& E, const int tidx) {
;     ...
;             PG8_LDA(At, 1, 1); PG8_STAGE(PG8_SB(1, 0), b3, voffB); PG8_STAGE(PG8_SB(1, 1), b3 + hstepB, voffB); PG8_STAGE(PG8_SA(1, 0), a3, voffA);
;             PG8_WAIT_V(8); PG8_WAIT_L(0); PG8_BAR; PG8_MMA(1, 0, At, B0); PG8_MMA(1, 1, At, B1); PG8_BAR; PG8_SCHED;
;     ...
;         if constexpr (ALIGN_EPI) { if (wr == 0) PG8_BAR; }
;         if constexpr (!Epi::AFTER_DRAIN) { E(acc, cur, wr, wc, fr, fq); S.done(cur); }
	s_add_i32 s11, s11, s36
	v_lshl_add_u64 v[202:203], v[202:203], 0, s[92:93]
	s_mov_b32 m0, s11
	ds_read_b128 v[170:173], v189 offset:49152
	ds_read_b128 v[174:177], v189 offset:50176
	ds_read_b128 v[178:181], v189 offset:51200
	ds_read_b128 v[182:185], v189 offset:52224
	ds_read_b128 v[190:193], v189 offset:53248
	ds_read_b128 v[194:197], v189 offset:54272
	ds_read_b128 v[198:201], v189 offset:55296
	ds_read_b128 v[222:225], v189 offset:56320
	global_load_lds_dwordx4 v[202:203], off
	s_add_i32 m0, s11, 0x2000
	s_add_u32 s28, s28, 0x200080
	v_lshl_add_u64 v[202:203], v[206:207], 0, s[92:93]
	s_addc_u32 s29, s29, 0
	s_add_i32 s11, s56, s36
	global_load_lds_dwordx4 v[202:203], off
	v_lshl_add_u64 v[202:203], s[28:29], 0, v[204:205]
	s_mov_b32 m0, s11
	s_nop 0
	global_load_lds_dwordx4 v[202:203], off
	v_lshl_add_u64 v[202:203], s[28:29], 0, v[148:149]
	s_add_i32 m0, s11, 0x2000
	s_nop 0
	global_load_lds_dwordx4 v[202:203], off
	v_lshl_add_u64 v[202:203], v[208:209], 0, s[92:93]
	s_mov_b32 m0, s82
	s_nop 0
	global_load_lds_dwordx4 v[202:203], off
	v_lshl_add_u64 v[202:203], v[226:227], 0, s[92:93]
	s_mov_b32 m0, s83
	s_nop 0
	global_load_lds_dwordx4 v[202:203], off
	s_waitcnt vmcnt(8)
	s_waitcnt lgkmcnt(0)
	s_barrier
	s_setprio 1
	s_waitcnt lgkmcnt(0)
	v_mfma_f32_16x16x32_bf16 v[60:63], v[128:131], v[170:173], v[60:63]
	v_mfma_f32_16x16x32_bf16 v[56:59], v[136:139], v[170:173], v[56:59]
	v_mfma_f32_16x16x32_bf16 v[44:47], v[128:131], v[178:181], v[44:47]
	v_mfma_f32_16x16x32_bf16 v[40:43], v[136:139], v[178:181], v[40:43]
	v_mfma_f32_16x16x32_bf16 v[28:31], v[128:131], v[190:193], v[28:31]
	v_mfma_f32_16x16x32_bf16 v[24:27], v[136:139], v[190:193], v[24:27]
	v_mfma_f32_16x16x32_bf16 v[12:15], v[128:131], v[198:201], v[12:15]
	v_mfma_f32_16x16x32_bf16 v[8:11], v[136:139], v[198:201], v[8:11]
	v_mfma_f32_16x16x32_bf16 v[60:63], v[132:135], v[174:177], v[60:63]
	v_mfma_f32_16x16x32_bf16 v[56:59], v[140:143], v[174:177], v[56:59]
	v_mfma_f32_16x16x32_bf16 v[44:47], v[132:135], v[182:185], v[44:47]
	v_mfma_f32_16x16x32_bf16 v[40:43], v[140:143], v[182:185], v[40:43]
	v_mfma_f32_16x16x32_bf16 v[28:31], v[132:135], v[194:197], v[28:31]
	v_mfma_f32_16x16x32_bf16 v[24:27], v[140:143], v[194:197], v[24:27]
	v_mfma_f32_16x16x32_bf16 v[12:15], v[132:135], v[222:225], v[12:15]
	v_mfma_f32_16x16x32_bf16 v[8:11], v[140:143], v[222:225], v[8:11]
	v_mfma_f32_16x16x32_bf16 v[52:55], v[154:157], v[170:173], v[52:55]
	v_mfma_f32_16x16x32_bf16 v[48:51], v[162:165], v[170:173], v[48:51]
	v_mfma_f32_16x16x32_bf16 v[36:39], v[154:157], v[178:181], v[36:39]
	v_mfma_f32_16x16x32_bf16 v[32:35], v[162:165], v[178:181], v[32:35]
	v_mfma_f32_16x16x32_bf16 v[20:23], v[154:157], v[190:193], v[20:23]
	v_mfma_f32_16x16x32_bf16 v[16:19], v[162:165], v[190:193], v[16:19]
	v_mfma_f32_16x16x32_bf16 v[4:7], v[154:157], v[198:201], v[4:7]
	v_mfma_f32_16x16x32_bf16 v[0:3], v[162:165], v[198:201], v[0:3]
	v_mfma_f32_16x16x32_bf16 v[52:55], v[158:161], v[174:177], v[52:55]
	v_mfma_f32_16x16x32_bf16 v[48:51], v[166:169], v[174:177], v[48:51]
	v_mfma_f32_16x16x32_bf16 v[36:39], v[158:161], v[182:185], v[36:39]
	v_mfma_f32_16x16x32_bf16 v[32:35], v[166:169], v[182:185], v[32:35]
	v_mfma_f32_16x16x32_bf16 v[20:23], v[158:161], v[194:197], v[20:23]
	v_mfma_f32_16x16x32_bf16 v[16:19], v[166:169], v[194:197], v[16:19]
	v_mfma_f32_16x16x32_bf16 v[4:7], v[158:161], v[222:225], v[4:7]
	v_mfma_f32_16x16x32_bf16 v[0:3], v[166:169], v[222:225], v[0:3]
	s_setprio 0
	s_barrier
	s_add_i32 s10, s10, 2
	s_add_u32 vcc_lo, vcc_lo, 0x100
	s_addc_u32 vcc_hi, vcc_hi, 0
	s_add_u32 s26, s26, 0x100
	s_addc_u32 s27, s27, 0
	s_cmpk_gt_u32 s10, 0x7d
	s_cbranch_scc0 .LBB0_112
	s_and_b64 vcc, exec, s[12:13]
	s_cbranch_vccz .LBB0_115
	s_barrier

; #define PG8_STAGE(bufoff, gbase, voff) do { _Pragma("unroll") for (int _i = 0; _i < 2; ++_i) \
;         __builtin_amdgcn_global_load_lds((const unsigned*)((const char*)(gbase) + (voff)[_i]), (LAS unsigned*)(lds + (bufoff) + ldsw + _i * 8192), 16, 0, 0); } while (0)
; #define PG8_LDA(dst, b, h) do { _Pragma("unroll") for (int m = 0; m < 4; ++m) _Pragma("unroll") for (int k = 0; k < 2; ++k) dst[m][k] = *(const LAS bf16x8*)(lds + PG8_SA(b, h) + aoff + m * 2048 + k * 1024); } while (0)
; #define PG8_LDB(dst, b, h) do { _Pragma("unroll") for (int n = 0; n < 2; ++n) _Pragma("unroll") for (int k = 0; k < 2; ++k) dst[n][k] = *(const LAS bf16x8*)(lds + PG8_SB(b, h) + boff + n * 2048 + k * 1024); } while (0)
; #define PG8_MMA(ai, bj, At, Bt) do { __builtin_amdgcn_s_setprio(1); _Pragma("unroll") for (int m = 0; m < 4; ++m) _Pragma("unroll") for (int n = 0; n < 2; ++n) _Pragma("unroll") for (int k = 0; k < 2; ++k) \
;         acc[ai][bj][m][n] = __builtin_amdgcn_mfma_f32_16x16x32_bf16(Bt[n][k], At[m][k], acc[ai][bj][m][n], 0, 0, 0); __builtin_amdgcn_s_setprio(0); } while (0)
; #define PG8_WAIT_V(n) asm volatile("s_waitcnt vmcnt(" #n ")" ::: "memory")
; #define PG8_WAIT_L(n) asm volatile("s_waitcnt lgkmcnt(" #n ")" ::: "memory")
; #define PG8_BAR __builtin_amdgcn_s_barrier()
; #define PG8_SCHED __builtin_amdgcn_sched_barrier(0)
; template <class Epi, class Sched, bool ALIGN_EPI = false, bool SP2 = false>
; DI void gemm_phase(LAS unsigned char* lds, const Gemm g, const Sched& S, const Epi& E, const int tidx) {
;     ...
;             PG8_LDB(B0, 0, 0); PG8_LDB(B1, 0, 1); PG8_SCHED; PG8_LDA(At, 0, 0); PG8_STAGE(PG8_SA(1, 1), a1 + hstepA, voffA);
;             PG8_WAIT_V(8); PG8_WAIT_L(0); PG8_BAR; PG8_MMA(0, 0, At, B0); PG8_MMA(0, 1, At, B1); PG8_BAR; PG8_SCHED;
;             PG8_LDA(At, 0, 1); PG8_STAGE(PG8_SB(0, 0), b2, voffB); PG8_STAGE(PG8_SB(0, 1), b2 + hstepB, voffB); PG8_STAGE(PG8_SA(0, 0), a2, voffA);
.LBB0_159:
	s_add_u32 s22, s20, 0xfff80080
	s_addc_u32 s23, s21, -1
	s_add_i32 s83, 0, 0x10000
	s_cmp_eq_u32 s82, 28
	s_cselect_b32 s25, s13, s23
	s_cselect_b32 s24, s54, s22
	v_add_u32_e32 v138, s83, v141
	s_cselect_b32 s23, s11, s57
	s_cselect_b32 s22, s55, s56
	s_add_i32 s91, 0, 0x14000
	ds_read_b128 v[146:149], v138
	ds_read_b128 v[150:153], v138 offset:1024
	ds_read_b128 v[154:157], v138 offset:2048
	ds_read_b128 v[158:161], v138 offset:3072
	v_add_u32_e32 v138, s91, v141
	ds_read_b128 v[162:165], v138
	ds_read_b128 v[166:169], v138 offset:1024
	ds_read_b128 v[170:173], v138 offset:2048
	ds_read_b128 v[174:177], v138 offset:3072
	v_lshl_add_u64 v[202:203], s[20:21], 0, v[134:135]
	s_add_i32 m0, s30, 0xc000
	ds_read_b128 v[178:181], v145
	ds_read_b128 v[182:185], v145 offset:1024
	ds_read_b128 v[186:189], v145 offset:2048
	ds_read_b128 v[190:193], v145 offset:3072
	ds_read_b128 v[194:197], v145 offset:4096
	ds_read_b128 v[198:201], v145 offset:5120
	ds_read_b128 v[222:225], v145 offset:6144
	ds_read_b128 v[226:229], v145 offset:7168
	global_load_lds_dwordx4 v[202:203], off
	v_lshl_add_u64 v[202:203], s[20:21], 0, v[136:137]
	s_add_i32 m0, s30, 0xe000
	s_nop 0
	global_load_lds_dwordx4 v[202:203], off
	s_waitcnt vmcnt(8)
	s_waitcnt lgkmcnt(0)
	s_barrier
	s_setprio 1
	s_waitcnt lgkmcnt(0)
	v_mfma_f32_16x16x32_bf16 v[124:127], v[146:149], v[178:181], v[124:127]
	v_mfma_f32_16x16x32_bf16 v[120:123], v[154:157], v[178:181], v[120:123]
	v_mfma_f32_16x16x32_bf16 v[108:111], v[146:149], v[186:189], v[108:111]
	v_mfma_f32_16x16x32_bf16 v[104:107], v[154:157], v[186:189], v[104:107]
	v_mfma_f32_16x16x32_bf16 v[92:95], v[146:149], v[194:197], v[92:95]
	v_mfma_f32_16x16x32_bf16 v[88:91], v[154:157], v[194:197], v[88:91]
	v_mfma_f32_16x16x32_bf16 v[76:79], v[146:149], v[222:225], v[76:79]
	v_mfma_f32_16x16x32_bf16 v[72:75], v[154:157], v[222:225], v[72:75]
	v_mfma_f32_16x16x32_bf16 v[124:127], v[150:153], v[182:185], v[124:127]
	v_mfma_f32_16x16x32_bf16 v[120:123], v[158:161], v[182:185], v[120:123]
	v_mfma_f32_16x16x32_bf16 v[108:111], v[150:153], v[190:193], v[108:111]
	v_mfma_f32_16x16x32_bf16 v[104:107], v[158:161], v[190:193], v[104:107]
	v_mfma_f32_16x16x32_bf16 v[92:95], v[150:153], v[198:201], v[92:95]
	v_mfma_f32_16x16x32_bf16 v[88:91], v[158:161], v[198:201], v[88:91]
	v_mfma_f32_16x16x32_bf16 v[76:79], v[150:153], v[226:229], v[76:79]
	v_mfma_f32_16x16x32_bf16 v[72:75], v[158:161], v[226:229], v[72:75]
	v_mfma_f32_16x16x32_bf16 v[116:119], v[162:165], v[178:181], v[116:119]
	v_mfma_f32_16x16x32_bf16 v[112:115], v[170:173], v[178:181], v[112:115]
	v_mfma_f32_16x16x32_bf16 v[100:103], v[162:165], v[186:189], v[100:103]
	v_mfma_f32_16x16x32_bf16 v[96:99], v[170:173], v[186:189], v[96:99]
	v_mfma_f32_16x16x32_bf16 v[84:87], v[162:165], v[194:197], v[84:87]
	v_mfma_f32_16x16x32_bf16 v[80:83], v[170:173], v[194:197], v[80:83]
	v_mfma_f32_16x16x32_bf16 v[68:71], v[162:165], v[222:225], v[68:71]
	v_mfma_f32_16x16x32_bf16 v[64:67], v[170:173], v[222:225], v[64:67]
	v_mfma_f32_16x16x32_bf16 v[116:119], v[166:169], v[182:185], v[116:119]
	v_mfma_f32_16x16x32_bf16 v[112:115], v[174:177], v[182:185], v[112:115]
	v_mfma_f32_16x16x32_bf16 v[100:103], v[166:169], v[190:193], v[100:103]
	v_mfma_f32_16x16x32_bf16 v[96:99], v[174:177], v[190:193], v[96:99]
	v_mfma_f32_16x16x32_bf16 v[84:87], v[166:169], v[198:201], v[84:87]
	v_mfma_f32_16x16x32_bf16 v[80:83], v[174:177], v[198:201], v[80:83]
	v_mfma_f32_16x16x32_bf16 v[68:71], v[166:169], v[226:229], v[68:71]
	v_mfma_f32_16x16x32_bf16 v[64:67], v[174:177], v[226:229], v[64:67]
	s_setprio 0
	s_barrier
	s_add_i32 s83, s83, s29
	v_lshl_add_u64 v[202:203], s[22:23], 0, v[204:205]
	s_mov_b32 m0, s83
	ds_read_b128 v[178:181], v145 offset:16384
	ds_read_b128 v[182:185], v145 offset:17408
	ds_read_b128 v[186:189], v145 offset:18432
	ds_read_b128 v[190:193], v145 offset:19456
	ds_read_b128 v[194:197], v145 offset:20480
	ds_read_b128 v[198:201], v145 offset:21504
	ds_read_b128 v[222:225], v145 offset:22528
	ds_read_b128 v[226:229], v145 offset:23552
	global_load_lds_dwordx4 v[202:203], off
	s_add_i32 m0, s83, 0x2000
	s_add_u32 vcc_lo, s22, 0x80000
	v_lshl_add_u64 v[206:207], s[22:23], 0, v[132:133]
	s_addc_u32 vcc_hi, s23, 0
	s_add_i32 s83, s91, s29
	global_load_lds_dwordx4 v[206:207], off
	v_lshl_add_u64 v[208:209], vcc, 0, v[204:205]
	s_mov_b32 m0, s83
	v_lshl_add_u64 v[230:231], s[24:25], 0, v[130:131]
	global_load_lds_dwordx4 v[208:209], off
	v_lshl_add_u64 v[208:209], vcc, 0, v[132:133]
	s_add_i32 m0, s83, 0x2000
	s_nop 0
	global_load_lds_dwordx4 v[208:209], off
	v_lshl_add_u64 v[208:209], s[24:25], 0, v[128:129]
	s_mov_b32 m0, s30
	s_nop 0
	global_load_lds_dwordx4 v[208:209], off
	s_mov_b32 m0, s31
	s_nop 0
	global_load_lds_dwordx4 v[230:231], off
	s_waitcnt vmcnt(8)
	s_waitcnt lgkmcnt(0)
	s_barrier
; #define PG8_STAGE(bufoff, gbase, voff) do { _Pragma("unroll") for (int _i = 0; _i < 2; ++_i) \
;         __builtin_amdgcn_global_load_lds((const unsigned*)((const char*)(gbase) + (voff)[_i]), (LAS unsigned*)(lds + (bufoff) + ldsw + _i * 8192), 16, 0, 0); } while (0)
; #define PG8_LDA(dst, b, h) do { _Pragma("unroll") for (int m = 0; m < 4; ++m) _Pragma("unroll") for (int k = 0; k < 2; ++k) dst[m][k] = *(const LAS bf16x8*)(lds + PG8_SA(b, h) + aoff + m * 2048 + k * 1024); } while (0)
; #define PG8_LDB(dst, b, h) do { _Pragma("unroll") for (int n = 0; n < 2; ++n) _Pragma("unroll") for (int k = 0; k < 2; ++k) dst[n][k] = *(const LAS bf16x8*)(lds + PG8_SB(b, h) + boff + n * 2048 + k * 1024); } while (0)
; #define PG8_MMA(ai, bj, At, Bt) do { __builtin_amdgcn_s_setprio(1); _Pragma("unroll") for (int m = 0; m < 4; ++m) _Pragma("unroll") for (int n = 0; n < 2; ++n) _Pragma("unroll") for (int k = 0; k < 2; ++k) \
;         acc[ai][bj][m][n] = __builtin_amdgcn_mfma_f32_16x16x32_bf16(Bt[n][k], At[m][k], acc[ai][bj][m][n], 0, 0, 0); __builtin_amdgcn_s_setprio(0); } while (0)
; #define PG8_WAIT_V(n) asm volatile("s_waitcnt vmcnt(" #n ")" ::: "memory")
; #define PG8_WAIT_L(n) asm volatile("s_waitcnt lgkmcnt(" #n ")" ::: "memory")
; #define PG8_BAR __builtin_amdgcn_s_barrier()
; #define PG8_SCHED __builtin_amdgcn_sched_barrier(0)
; template <class Epi, class Sched, bool ALIGN_EPI = false, bool SP2 = false>
; DI void gemm_phase(LAS unsigned char* lds, const Gemm g, const Sched& S, const Epi& E, const int tidx) {
;     ...
;             PG8_WAIT_V(8); PG8_WAIT_L(0); PG8_BAR; PG8_MMA(1, 0, At, B0); PG8_MMA(1, 1, At, B1); PG8_BAR; PG8_SCHED;
;             PG8_LDB(B0, 1, 0); PG8_LDB(B1, 1, 1); PG8_SCHED; PG8_LDA(At, 1, 0); PG8_STAGE(PG8_SA(0, 1), a2 + hstepA, voffA);
;             PG8_WAIT_V(8); PG8_WAIT_L(0); PG8_BAR; PG8_MMA(0, 0, At, B0); PG8_MMA(0, 1, At, B1); PG8_BAR; PG8_SCHED;
;             PG8_LDA(At, 1, 1); PG8_STAGE(PG8_SB(1, 0), b3, voffB); PG8_STAGE(PG8_SB(1, 1), b3 + hstepB, voffB); PG8_STAGE(PG8_SA(1, 0), a3, voffA);
	s_setprio 1
	s_waitcnt lgkmcnt(0)
	v_mfma_f32_16x16x32_bf16 v[60:63], v[146:149], v[178:181], v[60:63]
	v_mfma_f32_16x16x32_bf16 v[56:59], v[154:157], v[178:181], v[56:59]
	v_mfma_f32_16x16x32_bf16 v[44:47], v[146:149], v[186:189], v[44:47]
	v_mfma_f32_16x16x32_bf16 v[40:43], v[154:157], v[186:189], v[40:43]
	v_mfma_f32_16x16x32_bf16 v[28:31], v[146:149], v[194:197], v[28:31]
	v_mfma_f32_16x16x32_bf16 v[24:27], v[154:157], v[194:197], v[24:27]
	v_mfma_f32_16x16x32_bf16 v[12:15], v[146:149], v[222:225], v[12:15]
	v_mfma_f32_16x16x32_bf16 v[8:11], v[154:157], v[222:225], v[8:11]
	v_mfma_f32_16x16x32_bf16 v[60:63], v[150:153], v[182:185], v[60:63]
	v_mfma_f32_16x16x32_bf16 v[56:59], v[158:161], v[182:185], v[56:59]
	v_mfma_f32_16x16x32_bf16 v[44:47], v[150:153], v[190:193], v[44:47]
	v_mfma_f32_16x16x32_bf16 v[40:43], v[158:161], v[190:193], v[40:43]
	v_mfma_f32_16x16x32_bf16 v[28:31], v[150:153], v[198:201], v[28:31]
	v_mfma_f32_16x16x32_bf16 v[24:27], v[158:161], v[198:201], v[24:27]
	v_mfma_f32_16x16x32_bf16 v[12:15], v[150:153], v[226:229], v[12:15]
	v_mfma_f32_16x16x32_bf16 v[8:11], v[158:161], v[226:229], v[8:11]
	v_mfma_f32_16x16x32_bf16 v[52:55], v[162:165], v[178:181], v[52:55]
	v_mfma_f32_16x16x32_bf16 v[48:51], v[170:173], v[178:181], v[48:51]
	v_mfma_f32_16x16x32_bf16 v[36:39], v[162:165], v[186:189], v[36:39]
	v_mfma_f32_16x16x32_bf16 v[32:35], v[170:173], v[186:189], v[32:35]
	v_mfma_f32_16x16x32_bf16 v[20:23], v[162:165], v[194:197], v[20:23]
	v_mfma_f32_16x16x32_bf16 v[16:19], v[170:173], v[194:197], v[16:19]
	v_mfma_f32_16x16x32_bf16 v[4:7], v[162:165], v[222:225], v[4:7]
	v_mfma_f32_16x16x32_bf16 v[0:3], v[170:173], v[222:225], v[0:3]
	v_mfma_f32_16x16x32_bf16 v[52:55], v[166:169], v[182:185], v[52:55]
	v_mfma_f32_16x16x32_bf16 v[48:51], v[174:177], v[182:185], v[48:51]
	v_mfma_f32_16x16x32_bf16 v[36:39], v[166:169], v[190:193], v[36:39]
	v_mfma_f32_16x16x32_bf16 v[32:35], v[174:177], v[190:193], v[32:35]
	v_mfma_f32_16x16x32_bf16 v[20:23], v[166:169], v[198:201], v[20:23]
	v_mfma_f32_16x16x32_bf16 v[16:19], v[174:177], v[198:201], v[16:19]
	v_mfma_f32_16x16x32_bf16 v[4:7], v[166:169], v[226:229], v[4:7]
	v_mfma_f32_16x16x32_bf16 v[0:3], v[174:177], v[226:229], v[0:3]
	s_setprio 0
	s_barrier
	s_add_i32 s83, 0, 0x18000
	v_add_u32_e32 v138, s83, v141
	s_add_i32 s91, 0, 0x1c000
	ds_read_b128 v[146:149], v138
	ds_read_b128 v[150:153], v138 offset:1024
	ds_read_b128 v[154:157], v138 offset:2048
	ds_read_b128 v[158:161], v138 offset:3072
	v_add_u32_e32 v138, s91, v141
	ds_read_b128 v[162:165], v138
	ds_read_b128 v[166:169], v138 offset:1024
	ds_read_b128 v[170:173], v138 offset:2048
	ds_read_b128 v[174:177], v138 offset:3072
	s_add_u32 s24, s24, 0x80000
	s_addc_u32 s25, s25, 0
	s_mov_b32 m0, s34
	v_lshl_add_u64 v[232:233], s[24:25], 0, v[128:129]
	ds_read_b128 v[178:181], v145 offset:32768
	ds_read_b128 v[182:185], v145 offset:33792
	ds_read_b128 v[186:189], v145 offset:34816
	ds_read_b128 v[190:193], v145 offset:35840
	ds_read_b128 v[194:197], v145 offset:36864
	ds_read_b128 v[198:201], v145 offset:37888
	ds_read_b128 v[222:225], v145 offset:38912
	ds_read_b128 v[226:229], v145 offset:39936
	global_load_lds_dwordx4 v[232:233], off
	v_lshl_add_u64 v[232:233], s[24:25], 0, v[130:131]
	s_mov_b32 m0, s35
	s_nop 0
	global_load_lds_dwordx4 v[232:233], off
	s_waitcnt vmcnt(8)
	s_waitcnt lgkmcnt(0)
	s_barrier
	s_setprio 1
	s_waitcnt lgkmcnt(0)
	v_mfma_f32_16x16x32_bf16 v[124:127], v[146:149], v[178:181], v[124:127]
	v_mfma_f32_16x16x32_bf16 v[120:123], v[154:157], v[178:181], v[120:123]
	v_mfma_f32_16x16x32_bf16 v[108:111], v[146:149], v[186:189], v[108:111]
	v_mfma_f32_16x16x32_bf16 v[104:107], v[154:157], v[186:189], v[104:107]
	v_mfma_f32_16x16x32_bf16 v[92:95], v[146:149], v[194:197], v[92:95]
	v_mfma_f32_16x16x32_bf16 v[88:91], v[154:157], v[194:197], v[88:91]
	v_mfma_f32_16x16x32_bf16 v[76:79], v[146:149], v[222:225], v[76:79]
	v_mfma_f32_16x16x32_bf16 v[72:75], v[154:157], v[222:225], v[72:75]
	v_mfma_f32_16x16x32_bf16 v[124:127], v[150:153], v[182:185], v[124:127]
	v_mfma_f32_16x16x32_bf16 v[120:123], v[158:161], v[182:185], v[120:123]
	v_mfma_f32_16x16x32_bf16 v[108:111], v[150:153], v[190:193], v[108:111]
	v_mfma_f32_16x16x32_bf16 v[104:107], v[158:161], v[190:193], v[104:107]
	v_mfma_f32_16x16x32_bf16 v[92:95], v[150:153], v[198:201], v[92:95]
	v_mfma_f32_16x16x32_bf16 v[88:91], v[158:161], v[198:201], v[88:91]
	v_mfma_f32_16x16x32_bf16 v[76:79], v[150:153], v[226:229], v[76:79]
	v_mfma_f32_16x16x32_bf16 v[72:75], v[158:161], v[226:229], v[72:75]
	v_mfma_f32_16x16x32_bf16 v[116:119], v[162:165], v[178:181], v[116:119]
	v_mfma_f32_16x16x32_bf16 v[112:115], v[170:173], v[178:181], v[112:115]
	v_mfma_f32_16x16x32_bf16 v[100:103], v[162:165], v[186:189], v[100:103]
	v_mfma_f32_16x16x32_bf16 v[96:99], v[170:173], v[186:189], v[96:99]
	v_mfma_f32_16x16x32_bf16 v[84:87], v[162:165], v[194:197], v[84:87]
	v_mfma_f32_16x16x32_bf16 v[80:83], v[170:173], v[194:197], v[80:83]
	v_mfma_f32_16x16x32_bf16 v[68:71], v[162:165], v[222:225], v[68:71]
	v_mfma_f32_16x16x32_bf16 v[64:67], v[170:173], v[222:225], v[64:67]
	v_mfma_f32_16x16x32_bf16 v[116:119], v[166:169], v[182:185], v[116:119]
	v_mfma_f32_16x16x32_bf16 v[112:115], v[174:177], v[182:185], v[112:115]
	v_mfma_f32_16x16x32_bf16 v[100:103], v[166:169], v[190:193], v[100:103]
	v_mfma_f32_16x16x32_bf16 v[96:99], v[174:177], v[190:193], v[96:99]
	v_mfma_f32_16x16x32_bf16 v[84:87], v[166:169], v[198:201], v[84:87]
	v_mfma_f32_16x16x32_bf16 v[80:83], v[174:177], v[198:201], v[80:83]
	v_mfma_f32_16x16x32_bf16 v[68:71], v[166:169], v[226:229], v[68:71]
	v_mfma_f32_16x16x32_bf16 v[64:67], v[174:177], v[226:229], v[64:67]
	s_setprio 0
	s_barrier
; #define PG8_STAGE(bufoff, gbase, voff) do { _Pragma("unroll") for (int _i = 0; _i < 2; ++_i) \
;         __builtin_amdgcn_global_load_lds((const unsigned*)((const char*)(gbase) + (voff)[_i]), (LAS unsigned*)(lds + (bufoff) + ldsw + _i * 8192), 16, 0, 0); } while (0)
; #define PG8_LDA(dst, b, h) do { _Pragma("unroll") for (int m = 0; m < 4; ++m) _Pragma("unroll") for (int k = 0; k < 2; ++k) dst[m][k] = *(const LAS bf16x8*)(lds + PG8_SA(b, h) + aoff + m * 2048 + k * 1024); } while (0)
; #define PG8_MMA(ai, bj, At, Bt) do { __builtin_amdgcn_s_setprio(1); _Pragma("unroll") for (int m = 0; m < 4; ++m) _Pragma("unroll") for (int n = 0; n < 2; ++n) _Pragma("unroll") for (int k = 0; k < 2; ++k) \
;         acc[ai][bj][m][n] = __builtin_amdgcn_mfma_f32_16x16x32_bf16(Bt[n][k], At[m][k], acc[ai][bj][m][n], 0, 0, 0); __builtin_amdgcn_s_setprio(0); } while (0)
; #define PG8_WAIT_V(n) asm volatile("s_waitcnt vmcnt(" #n ")" ::: "memory")
; #define PG8_WAIT_L(n) asm volatile("s_waitcnt lgkmcnt(" #n ")" ::: "memory")
; #define PG8_BAR __builtin_amdgcn_s_barrier()
; #define PG8_SCHED __builtin_amdgcn_sched_barrier(0)
; template <class Epi, class Sched, bool ALIGN_EPI = false, bool SP2 = false>
; DI void gemm_phase(LAS unsigned char* lds, const Gemm g, const Sched& S, const Epi& E, const int tidx) {
;     ...
;             PG8_LDA(At, 1, 1); PG8_STAGE(PG8_SB(1, 0), b3, voffB); PG8_STAGE(PG8_SB(1, 1), b3 + hstepB, voffB); PG8_STAGE(PG8_SA(1, 0), a3, voffA);
;             PG8_WAIT_V(8); PG8_WAIT_L(0); PG8_BAR; PG8_MMA(1, 0, At, B0); PG8_MMA(1, 1, At, B1); PG8_BAR; PG8_SCHED;
;     ...
;         if constexpr (ALIGN_EPI) { if (wr == 0) PG8_BAR; }
;         if constexpr (!Epi::AFTER_DRAIN) { E(acc, cur, wr, wc, fr, fq); S.done(cur); }
	s_add_i32 s24, s83, s29
	v_lshl_add_u64 v[202:203], v[202:203], 0, s[92:93]
	s_mov_b32 m0, s24
	ds_read_b128 v[178:181], v145 offset:49152
	ds_read_b128 v[182:185], v145 offset:50176
	ds_read_b128 v[186:189], v145 offset:51200
	ds_read_b128 v[190:193], v145 offset:52224
	ds_read_b128 v[194:197], v145 offset:53248
	ds_read_b128 v[198:201], v145 offset:54272
	ds_read_b128 v[222:225], v145 offset:55296
	ds_read_b128 v[226:229], v145 offset:56320
	global_load_lds_dwordx4 v[202:203], off
	s_add_i32 m0, s24, 0x2000
	s_add_u32 s22, s22, 0x80080
	v_lshl_add_u64 v[202:203], v[206:207], 0, s[92:93]
	s_addc_u32 s23, s23, 0
	s_add_i32 s24, s91, s29
	global_load_lds_dwordx4 v[202:203], off
	v_lshl_add_u64 v[202:203], s[22:23], 0, v[204:205]
	s_mov_b32 m0, s24
	s_nop 0
	global_load_lds_dwordx4 v[202:203], off
	v_lshl_add_u64 v[202:203], s[22:23], 0, v[132:133]
	s_add_i32 m0, s24, 0x2000
	s_nop 0
	global_load_lds_dwordx4 v[202:203], off
	v_lshl_add_u64 v[202:203], v[208:209], 0, s[92:93]
	s_mov_b32 m0, s36
	s_nop 0
	global_load_lds_dwordx4 v[202:203], off
	v_lshl_add_u64 v[202:203], v[230:231], 0, s[92:93]
	s_mov_b32 m0, s37
	s_nop 0
	global_load_lds_dwordx4 v[202:203], off
	s_waitcnt vmcnt(8)
	s_waitcnt lgkmcnt(0)
	s_barrier
	s_setprio 1
	s_waitcnt lgkmcnt(0)
	v_mfma_f32_16x16x32_bf16 v[60:63], v[146:149], v[178:181], v[60:63]
	v_mfma_f32_16x16x32_bf16 v[56:59], v[154:157], v[178:181], v[56:59]
	v_mfma_f32_16x16x32_bf16 v[44:47], v[146:149], v[186:189], v[44:47]
	v_mfma_f32_16x16x32_bf16 v[40:43], v[154:157], v[186:189], v[40:43]
	v_mfma_f32_16x16x32_bf16 v[28:31], v[146:149], v[194:197], v[28:31]
	v_mfma_f32_16x16x32_bf16 v[24:27], v[154:157], v[194:197], v[24:27]
	v_mfma_f32_16x16x32_bf16 v[12:15], v[146:149], v[222:225], v[12:15]
	v_mfma_f32_16x16x32_bf16 v[8:11], v[154:157], v[222:225], v[8:11]
	v_mfma_f32_16x16x32_bf16 v[60:63], v[150:153], v[182:185], v[60:63]
	v_mfma_f32_16x16x32_bf16 v[56:59], v[158:161], v[182:185], v[56:59]
	v_mfma_f32_16x16x32_bf16 v[44:47], v[150:153], v[190:193], v[44:47]
	v_mfma_f32_16x16x32_bf16 v[40:43], v[158:161], v[190:193], v[40:43]
	v_mfma_f32_16x16x32_bf16 v[28:31], v[150:153], v[198:201], v[28:31]
	v_mfma_f32_16x16x32_bf16 v[24:27], v[158:161], v[198:201], v[24:27]
	v_mfma_f32_16x16x32_bf16 v[12:15], v[150:153], v[226:229], v[12:15]
	v_mfma_f32_16x16x32_bf16 v[8:11], v[158:161], v[226:229], v[8:11]
	v_mfma_f32_16x16x32_bf16 v[52:55], v[162:165], v[178:181], v[52:55]
	v_mfma_f32_16x16x32_bf16 v[48:51], v[170:173], v[178:181], v[48:51]
	v_mfma_f32_16x16x32_bf16 v[36:39], v[162:165], v[186:189], v[36:39]
	v_mfma_f32_16x16x32_bf16 v[32:35], v[170:173], v[186:189], v[32:35]
	v_mfma_f32_16x16x32_bf16 v[20:23], v[162:165], v[194:197], v[20:23]
	v_mfma_f32_16x16x32_bf16 v[16:19], v[170:173], v[194:197], v[16:19]
	v_mfma_f32_16x16x32_bf16 v[4:7], v[162:165], v[222:225], v[4:7]
	v_mfma_f32_16x16x32_bf16 v[0:3], v[170:173], v[222:225], v[0:3]
	v_mfma_f32_16x16x32_bf16 v[52:55], v[166:169], v[182:185], v[52:55]
	v_mfma_f32_16x16x32_bf16 v[48:51], v[174:177], v[182:185], v[48:51]
	v_mfma_f32_16x16x32_bf16 v[36:39], v[166:169], v[190:193], v[36:39]
	v_mfma_f32_16x16x32_bf16 v[32:35], v[174:177], v[190:193], v[32:35]
	v_mfma_f32_16x16x32_bf16 v[20:23], v[166:169], v[198:201], v[20:23]
	v_mfma_f32_16x16x32_bf16 v[16:19], v[174:177], v[198:201], v[16:19]
	v_mfma_f32_16x16x32_bf16 v[4:7], v[166:169], v[226:229], v[4:7]
	v_mfma_f32_16x16x32_bf16 v[0:3], v[174:177], v[226:229], v[0:3]
	s_setprio 0
	s_barrier
	s_add_i32 s82, s82, 2
	s_add_u32 s56, s56, 0x100
	s_addc_u32 s57, s57, 0
	s_add_u32 s20, s20, 0x100
	s_addc_u32 s21, s21, 0
	s_cmp_gt_u32 s82, 29
	s_cbranch_scc0 .LBB0_159
	s_and_b64 vcc, exec, s[6:7]
	s_cbranch_vccz .LBB0_162
	s_barrier

; #define PG8_STAGE(bufoff, gbase, voff) do { _Pragma("unroll") for (int _i = 0; _i < 2; ++_i) \
;         __builtin_amdgcn_global_load_lds((const unsigned*)((const char*)(gbase) + (voff)[_i]), (LAS unsigned*)(lds + (bufoff) + ldsw + _i * 8192), 16, 0, 0); } while (0)
; #define PG8_LDA(dst, b, h) do { _Pragma("unroll") for (int m = 0; m < 4; ++m) _Pragma("unroll") for (int k = 0; k < 2; ++k) dst[m][k] = *(const LAS bf16x8*)(lds + PG8_SA(b, h) + aoff + m * 2048 + k * 1024); } while (0)
; #define PG8_LDB(dst, b, h) do { _Pragma("unroll") for (int n = 0; n < 2; ++n) _Pragma("unroll") for (int k = 0; k < 2; ++k) dst[n][k] = *(const LAS bf16x8*)(lds + PG8_SB(b, h) + boff + n * 2048 + k * 1024); } while (0)
; #define PG8_MMA(ai, bj, At, Bt) do { __builtin_amdgcn_s_setprio(1); _Pragma("unroll") for (int m = 0; m < 4; ++m) _Pragma("unroll") for (int n = 0; n < 2; ++n) _Pragma("unroll") for (int k = 0; k < 2; ++k) \
;         acc[ai][bj][m][n] = __builtin_amdgcn_mfma_f32_16x16x32_bf16(Bt[n][k], At[m][k], acc[ai][bj][m][n], 0, 0, 0); __builtin_amdgcn_s_setprio(0); } while (0)
; #define PG8_WAIT_V(n) asm volatile("s_waitcnt vmcnt(" #n ")" ::: "memory")
; #define PG8_WAIT_L(n) asm volatile("s_waitcnt lgkmcnt(" #n ")" ::: "memory")
; #define PG8_BAR __builtin_amdgcn_s_barrier()
; #define PG8_SCHED __builtin_amdgcn_sched_barrier(0)
; template <class Epi, class Sched, bool ALIGN_EPI = false, bool SP2 = false>
; DI void gemm_phase(LAS unsigned char* lds, const Gemm g, const Sched& S, const Epi& E, const int tidx) {
;     ...
;             PG8_LDB(B0, 0, 0); PG8_LDB(B1, 0, 1); PG8_SCHED; PG8_LDA(At, 0, 0); PG8_STAGE(PG8_SA(1, 1), a1 + hstepA, voffA);
;             PG8_WAIT_V(8); PG8_WAIT_L(0); PG8_BAR; PG8_MMA(0, 0, At, B0); PG8_MMA(0, 1, At, B1); PG8_BAR; PG8_SCHED;
;             PG8_LDA(At, 0, 1); PG8_STAGE(PG8_SB(0, 0), b2, voffB); PG8_STAGE(PG8_SB(0, 1), b2 + hstepB, voffB); PG8_STAGE(PG8_SA(0, 0), a2, voffA);
;             PG8_WAIT_V(8); PG8_WAIT_L(0); PG8_BAR; PG8_MMA(1, 0, At, B0); PG8_MMA(1, 1, At, B1); PG8_BAR; PG8_SCHED;
.LBB0_190:
	s_add_u32 s4, s20, 0x100
	s_addc_u32 s5, s21, 0
	s_add_i32 s91, 0, 0x10000
	s_cmp_eq_u32 s83, 28
	s_cselect_b32 s25, s15, s5
	s_cselect_b32 s24, s14, s4
	s_cselect_b32 s23, s13, s82
	s_cselect_b32 s22, s19, s57
	s_add_i32 s97, 0, 0x14000
	v_add_u32_e32 v140, s91, v221
	v_add_u32_e32 v156, s97, v221
	ds_read_b128 v[128:131], v140
	ds_read_b128 v[132:135], v140 offset:1024
	ds_read_b128 v[136:139], v140 offset:2048
	ds_read_b128 v[140:143], v140 offset:3072
	ds_read_b128 v[144:147], v156
	ds_read_b128 v[148:151], v156 offset:1024
	ds_read_b128 v[152:155], v156 offset:2048
	ds_read_b128 v[156:159], v156 offset:3072
	v_lshl_add_u64 v[202:203], s[20:21], 0, v[190:191]
	s_add_i32 m0, s30, 0xc000
	ds_read_b128 v[160:163], v229
	ds_read_b128 v[164:167], v229 offset:1024
	ds_read_b128 v[168:171], v229 offset:2048
	ds_read_b128 v[172:175], v229 offset:3072
	ds_read_b128 v[176:179], v229 offset:4096
	ds_read_b128 v[180:183], v229 offset:5120
	ds_read_b128 v[194:197], v229 offset:6144
	ds_read_b128 v[198:201], v229 offset:7168
	global_load_lds_dwordx4 v[202:203], off
	v_lshl_add_u64 v[202:203], s[20:21], 0, v[192:193]
	s_add_i32 m0, s30, 0xe000
	s_nop 0
	global_load_lds_dwordx4 v[202:203], off
	s_waitcnt vmcnt(8)
	s_waitcnt lgkmcnt(0)
	s_barrier
	s_setprio 1
	s_waitcnt lgkmcnt(0)
	v_mfma_f32_16x16x32_bf16 v[124:127], v[128:131], v[160:163], v[124:127]
	v_mfma_f32_16x16x32_bf16 v[120:123], v[136:139], v[160:163], v[120:123]
	v_mfma_f32_16x16x32_bf16 v[108:111], v[128:131], v[168:171], v[108:111]
	v_mfma_f32_16x16x32_bf16 v[104:107], v[136:139], v[168:171], v[104:107]
	v_mfma_f32_16x16x32_bf16 v[92:95], v[128:131], v[176:179], v[92:95]
	v_mfma_f32_16x16x32_bf16 v[88:91], v[136:139], v[176:179], v[88:91]
	v_mfma_f32_16x16x32_bf16 v[76:79], v[128:131], v[194:197], v[76:79]
	v_mfma_f32_16x16x32_bf16 v[72:75], v[136:139], v[194:197], v[72:75]
	v_mfma_f32_16x16x32_bf16 v[124:127], v[132:135], v[164:167], v[124:127]
	v_mfma_f32_16x16x32_bf16 v[120:123], v[140:143], v[164:167], v[120:123]
	v_mfma_f32_16x16x32_bf16 v[108:111], v[132:135], v[172:175], v[108:111]
	v_mfma_f32_16x16x32_bf16 v[104:107], v[140:143], v[172:175], v[104:107]
	v_mfma_f32_16x16x32_bf16 v[92:95], v[132:135], v[180:183], v[92:95]
	v_mfma_f32_16x16x32_bf16 v[88:91], v[140:143], v[180:183], v[88:91]
	v_mfma_f32_16x16x32_bf16 v[76:79], v[132:135], v[198:201], v[76:79]
	v_mfma_f32_16x16x32_bf16 v[72:75], v[140:143], v[198:201], v[72:75]
	v_mfma_f32_16x16x32_bf16 v[116:119], v[144:147], v[160:163], v[116:119]
	v_mfma_f32_16x16x32_bf16 v[112:115], v[152:155], v[160:163], v[112:115]
	v_mfma_f32_16x16x32_bf16 v[100:103], v[144:147], v[168:171], v[100:103]
	v_mfma_f32_16x16x32_bf16 v[96:99], v[152:155], v[168:171], v[96:99]
	v_mfma_f32_16x16x32_bf16 v[84:87], v[144:147], v[176:179], v[84:87]
	v_mfma_f32_16x16x32_bf16 v[80:83], v[152:155], v[176:179], v[80:83]
	v_mfma_f32_16x16x32_bf16 v[68:71], v[144:147], v[194:197], v[68:71]
	v_mfma_f32_16x16x32_bf16 v[64:67], v[152:155], v[194:197], v[64:67]
	v_mfma_f32_16x16x32_bf16 v[116:119], v[148:151], v[164:167], v[116:119]
	v_mfma_f32_16x16x32_bf16 v[112:115], v[156:159], v[164:167], v[112:115]
	v_mfma_f32_16x16x32_bf16 v[100:103], v[148:151], v[172:175], v[100:103]
	v_mfma_f32_16x16x32_bf16 v[96:99], v[156:159], v[172:175], v[96:99]
	v_mfma_f32_16x16x32_bf16 v[84:87], v[148:151], v[180:183], v[84:87]
	v_mfma_f32_16x16x32_bf16 v[80:83], v[156:159], v[180:183], v[80:83]
	v_mfma_f32_16x16x32_bf16 v[68:71], v[148:151], v[198:201], v[68:71]
	v_mfma_f32_16x16x32_bf16 v[64:67], v[156:159], v[198:201], v[64:67]
	s_setprio 0
	s_barrier
	s_add_i32 s20, s91, s29
	v_lshl_add_u64 v[202:203], s[22:23], 0, v[204:205]
	s_mov_b32 m0, s20
	ds_read_b128 v[160:163], v229 offset:16384
	ds_read_b128 v[164:167], v229 offset:17408
	ds_read_b128 v[168:171], v229 offset:18432
	ds_read_b128 v[172:175], v229 offset:19456
	ds_read_b128 v[176:179], v229 offset:20480
	ds_read_b128 v[180:183], v229 offset:21504
	ds_read_b128 v[194:197], v229 offset:22528
	ds_read_b128 v[198:201], v229 offset:23552
	global_load_lds_dwordx4 v[202:203], off
	s_add_i32 m0, s20, 0x2000
	s_add_u32 s20, s22, 0x80000
	v_lshl_add_u64 v[206:207], s[22:23], 0, v[188:189]
	s_addc_u32 s21, s23, 0
	s_add_i32 s91, s97, s29
	global_load_lds_dwordx4 v[206:207], off
	v_lshl_add_u64 v[208:209], s[20:21], 0, v[204:205]
	s_mov_b32 m0, s91
	v_lshl_add_u64 v[222:223], s[24:25], 0, v[186:187]
	global_load_lds_dwordx4 v[208:209], off
	v_lshl_add_u64 v[208:209], s[20:21], 0, v[188:189]
	s_add_i32 m0, s91, 0x2000
	s_nop 0
	global_load_lds_dwordx4 v[208:209], off
	v_lshl_add_u64 v[208:209], s[24:25], 0, v[184:185]
	s_mov_b32 m0, s30
	s_nop 0
	global_load_lds_dwordx4 v[208:209], off
	s_mov_b32 m0, s31
	s_nop 0
	global_load_lds_dwordx4 v[222:223], off
	s_waitcnt vmcnt(8)
	s_waitcnt lgkmcnt(0)
	s_barrier
; #define PG8_STAGE(bufoff, gbase, voff) do { _Pragma("unroll") for (int _i = 0; _i < 2; ++_i) \
;         __builtin_amdgcn_global_load_lds((const unsigned*)((const char*)(gbase) + (voff)[_i]), (LAS unsigned*)(lds + (bufoff) + ldsw + _i * 8192), 16, 0, 0); } while (0)
; #define PG8_LDA(dst, b, h) do { _Pragma("unroll") for (int m = 0; m < 4; ++m) _Pragma("unroll") for (int k = 0; k < 2; ++k) dst[m][k] = *(const LAS bf16x8*)(lds + PG8_SA(b, h) + aoff + m * 2048 + k * 1024); } while (0)
; #define PG8_LDB(dst, b, h) do { _Pragma("unroll") for (int n = 0; n < 2; ++n) _Pragma("unroll") for (int k = 0; k < 2; ++k) dst[n][k] = *(const LAS bf16x8*)(lds + PG8_SB(b, h) + boff + n * 2048 + k * 1024); } while (0)
; #define PG8_MMA(ai, bj, At, Bt) do { __builtin_amdgcn_s_setprio(1); _Pragma("unroll") for (int m = 0; m < 4; ++m) _Pragma("unroll") for (int n = 0; n < 2; ++n) _Pragma("unroll") for (int k = 0; k < 2; ++k) \
;         acc[ai][bj][m][n] = __builtin_amdgcn_mfma_f32_16x16x32_bf16(Bt[n][k], At[m][k], acc[ai][bj][m][n], 0, 0, 0); __builtin_amdgcn_s_setprio(0); } while (0)
; #define PG8_WAIT_V(n) asm volatile("s_waitcnt vmcnt(" #n ")" ::: "memory")
; #define PG8_WAIT_L(n) asm volatile("s_waitcnt lgkmcnt(" #n ")" ::: "memory")
; #define PG8_BAR __builtin_amdgcn_s_barrier()
; #define PG8_SCHED __builtin_amdgcn_sched_barrier(0)
; template <class Epi, class Sched, bool ALIGN_EPI = false, bool SP2 = false>
; DI void gemm_phase(LAS unsigned char* lds, const Gemm g, const Sched& S, const Epi& E, const int tidx) {
;     ...
;             PG8_WAIT_V(8); PG8_WAIT_L(0); PG8_BAR; PG8_MMA(1, 0, At, B0); PG8_MMA(1, 1, At, B1); PG8_BAR; PG8_SCHED;
;             PG8_LDB(B0, 1, 0); PG8_LDB(B1, 1, 1); PG8_SCHED; PG8_LDA(At, 1, 0); PG8_STAGE(PG8_SA(0, 1), a2 + hstepA, voffA);
;             PG8_WAIT_V(8); PG8_WAIT_L(0); PG8_BAR; PG8_MMA(0, 0, At, B0); PG8_MMA(0, 1, At, B1); PG8_BAR; PG8_SCHED;
;             PG8_LDA(At, 1, 1); PG8_STAGE(PG8_SB(1, 0), b3, voffB); PG8_STAGE(PG8_SB(1, 1), b3 + hstepB, voffB); PG8_STAGE(PG8_SA(1, 0), a3, voffA);
	s_setprio 1
	s_waitcnt lgkmcnt(0)
	v_mfma_f32_16x16x32_bf16 v[60:63], v[128:131], v[160:163], v[60:63]
	v_mfma_f32_16x16x32_bf16 v[56:59], v[136:139], v[160:163], v[56:59]
	v_mfma_f32_16x16x32_bf16 v[44:47], v[128:131], v[168:171], v[44:47]
	v_mfma_f32_16x16x32_bf16 v[40:43], v[136:139], v[168:171], v[40:43]
	v_mfma_f32_16x16x32_bf16 v[28:31], v[128:131], v[176:179], v[28:31]
	v_mfma_f32_16x16x32_bf16 v[24:27], v[136:139], v[176:179], v[24:27]
	v_mfma_f32_16x16x32_bf16 v[12:15], v[128:131], v[194:197], v[12:15]
	v_mfma_f32_16x16x32_bf16 v[8:11], v[136:139], v[194:197], v[8:11]
	v_mfma_f32_16x16x32_bf16 v[60:63], v[132:135], v[164:167], v[60:63]
	v_mfma_f32_16x16x32_bf16 v[56:59], v[140:143], v[164:167], v[56:59]
	v_mfma_f32_16x16x32_bf16 v[44:47], v[132:135], v[172:175], v[44:47]
	v_mfma_f32_16x16x32_bf16 v[40:43], v[140:143], v[172:175], v[40:43]
	v_mfma_f32_16x16x32_bf16 v[28:31], v[132:135], v[180:183], v[28:31]
	v_mfma_f32_16x16x32_bf16 v[24:27], v[140:143], v[180:183], v[24:27]
	v_mfma_f32_16x16x32_bf16 v[12:15], v[132:135], v[198:201], v[12:15]
	v_mfma_f32_16x16x32_bf16 v[8:11], v[140:143], v[198:201], v[8:11]
	v_mfma_f32_16x16x32_bf16 v[52:55], v[144:147], v[160:163], v[52:55]
	v_mfma_f32_16x16x32_bf16 v[48:51], v[152:155], v[160:163], v[48:51]
	v_mfma_f32_16x16x32_bf16 v[36:39], v[144:147], v[168:171], v[36:39]
	v_mfma_f32_16x16x32_bf16 v[32:35], v[152:155], v[168:171], v[32:35]
	v_mfma_f32_16x16x32_bf16 v[20:23], v[144:147], v[176:179], v[20:23]
	v_mfma_f32_16x16x32_bf16 v[16:19], v[152:155], v[176:179], v[16:19]
	v_mfma_f32_16x16x32_bf16 v[4:7], v[144:147], v[194:197], v[4:7]
	v_mfma_f32_16x16x32_bf16 v[0:3], v[152:155], v[194:197], v[0:3]
	v_mfma_f32_16x16x32_bf16 v[52:55], v[148:151], v[164:167], v[52:55]
	v_mfma_f32_16x16x32_bf16 v[48:51], v[156:159], v[164:167], v[48:51]
	v_mfma_f32_16x16x32_bf16 v[36:39], v[148:151], v[172:175], v[36:39]
	v_mfma_f32_16x16x32_bf16 v[32:35], v[156:159], v[172:175], v[32:35]
	v_mfma_f32_16x16x32_bf16 v[20:23], v[148:151], v[180:183], v[20:23]
	v_mfma_f32_16x16x32_bf16 v[16:19], v[156:159], v[180:183], v[16:19]
	v_mfma_f32_16x16x32_bf16 v[4:7], v[148:151], v[198:201], v[4:7]
	v_mfma_f32_16x16x32_bf16 v[0:3], v[156:159], v[198:201], v[0:3]
	s_setprio 0
	s_barrier
	s_add_i32 s91, 0, 0x18000
	s_add_i32 s97, 0, 0x1c000
	v_add_u32_e32 v140, s91, v221
	v_add_u32_e32 v156, s97, v221
	ds_read_b128 v[128:131], v140
	ds_read_b128 v[132:135], v140 offset:1024
	ds_read_b128 v[136:139], v140 offset:2048
	ds_read_b128 v[140:143], v140 offset:3072
	ds_read_b128 v[144:147], v156
	ds_read_b128 v[148:151], v156 offset:1024
	ds_read_b128 v[152:155], v156 offset:2048
	ds_read_b128 v[156:159], v156 offset:3072
	s_add_u32 s20, s24, 0x1b0000
	s_addc_u32 s21, s25, 0
	s_mov_b32 m0, s34
	v_lshl_add_u64 v[224:225], s[20:21], 0, v[184:185]
	ds_read_b128 v[160:163], v229 offset:32768
	ds_read_b128 v[164:167], v229 offset:33792
	ds_read_b128 v[168:171], v229 offset:34816
	ds_read_b128 v[172:175], v229 offset:35840
	ds_read_b128 v[176:179], v229 offset:36864
	ds_read_b128 v[180:183], v229 offset:37888
	ds_read_b128 v[194:197], v229 offset:38912
	ds_read_b128 v[198:201], v229 offset:39936
	global_load_lds_dwordx4 v[224:225], off
	v_lshl_add_u64 v[224:225], s[20:21], 0, v[186:187]
	s_mov_b32 m0, s35
	s_nop 0
	global_load_lds_dwordx4 v[224:225], off
	s_waitcnt vmcnt(8)
	s_waitcnt lgkmcnt(0)
	s_barrier
	s_setprio 1
	s_waitcnt lgkmcnt(0)
	v_mfma_f32_16x16x32_bf16 v[124:127], v[128:131], v[160:163], v[124:127]
	v_mfma_f32_16x16x32_bf16 v[120:123], v[136:139], v[160:163], v[120:123]
	v_mfma_f32_16x16x32_bf16 v[108:111], v[128:131], v[168:171], v[108:111]
	v_mfma_f32_16x16x32_bf16 v[104:107], v[136:139], v[168:171], v[104:107]
	v_mfma_f32_16x16x32_bf16 v[92:95], v[128:131], v[176:179], v[92:95]
	v_mfma_f32_16x16x32_bf16 v[88:91], v[136:139], v[176:179], v[88:91]
	v_mfma_f32_16x16x32_bf16 v[76:79], v[128:131], v[194:197], v[76:79]
	v_mfma_f32_16x16x32_bf16 v[72:75], v[136:139], v[194:197], v[72:75]
	v_mfma_f32_16x16x32_bf16 v[124:127], v[132:135], v[164:167], v[124:127]
	v_mfma_f32_16x16x32_bf16 v[120:123], v[140:143], v[164:167], v[120:123]
	v_mfma_f32_16x16x32_bf16 v[108:111], v[132:135], v[172:175], v[108:111]
	v_mfma_f32_16x16x32_bf16 v[104:107], v[140:143], v[172:175], v[104:107]
	v_mfma_f32_16x16x32_bf16 v[92:95], v[132:135], v[180:183], v[92:95]
	v_mfma_f32_16x16x32_bf16 v[88:91], v[140:143], v[180:183], v[88:91]
	v_mfma_f32_16x16x32_bf16 v[76:79], v[132:135], v[198:201], v[76:79]
	v_mfma_f32_16x16x32_bf16 v[72:75], v[140:143], v[198:201], v[72:75]
	v_mfma_f32_16x16x32_bf16 v[116:119], v[144:147], v[160:163], v[116:119]
	v_mfma_f32_16x16x32_bf16 v[112:115], v[152:155], v[160:163], v[112:115]
	v_mfma_f32_16x16x32_bf16 v[100:103], v[144:147], v[168:171], v[100:103]
	v_mfma_f32_16x16x32_bf16 v[96:99], v[152:155], v[168:171], v[96:99]
	v_mfma_f32_16x16x32_bf16 v[84:87], v[144:147], v[176:179], v[84:87]
	v_mfma_f32_16x16x32_bf16 v[80:83], v[152:155], v[176:179], v[80:83]
	v_mfma_f32_16x16x32_bf16 v[68:71], v[144:147], v[194:197], v[68:71]
	v_mfma_f32_16x16x32_bf16 v[64:67], v[152:155], v[194:197], v[64:67]
	v_mfma_f32_16x16x32_bf16 v[116:119], v[148:151], v[164:167], v[116:119]
	v_mfma_f32_16x16x32_bf16 v[112:115], v[156:159], v[164:167], v[112:115]
	v_mfma_f32_16x16x32_bf16 v[100:103], v[148:151], v[172:175], v[100:103]
	v_mfma_f32_16x16x32_bf16 v[96:99], v[156:159], v[172:175], v[96:99]
	v_mfma_f32_16x16x32_bf16 v[84:87], v[148:151], v[180:183], v[84:87]
	v_mfma_f32_16x16x32_bf16 v[80:83], v[156:159], v[180:183], v[80:83]
	v_mfma_f32_16x16x32_bf16 v[68:71], v[148:151], v[198:201], v[68:71]
	v_mfma_f32_16x16x32_bf16 v[64:67], v[156:159], v[198:201], v[64:67]
	s_setprio 0
	s_barrier
; #define PG8_STAGE(bufoff, gbase, voff) do { _Pragma("unroll") for (int _i = 0; _i < 2; ++_i) \
;         __builtin_amdgcn_global_load_lds((const unsigned*)((const char*)(gbase) + (voff)[_i]), (LAS unsigned*)(lds + (bufoff) + ldsw + _i * 8192), 16, 0, 0); } while (0)
; #define PG8_LDA(dst, b, h) do { _Pragma("unroll") for (int m = 0; m < 4; ++m) _Pragma("unroll") for (int k = 0; k < 2; ++k) dst[m][k] = *(const LAS bf16x8*)(lds + PG8_SA(b, h) + aoff + m * 2048 + k * 1024); } while (0)
; #define PG8_MMA(ai, bj, At, Bt) do { __builtin_amdgcn_s_setprio(1); _Pragma("unroll") for (int m = 0; m < 4; ++m) _Pragma("unroll") for (int n = 0; n < 2; ++n) _Pragma("unroll") for (int k = 0; k < 2; ++k) \
;         acc[ai][bj][m][n] = __builtin_amdgcn_mfma_f32_16x16x32_bf16(Bt[n][k], At[m][k], acc[ai][bj][m][n], 0, 0, 0); __builtin_amdgcn_s_setprio(0); } while (0)
; #define PG8_WAIT_V(n) asm volatile("s_waitcnt vmcnt(" #n ")" ::: "memory")
; #define PG8_WAIT_L(n) asm volatile("s_waitcnt lgkmcnt(" #n ")" ::: "memory")
; #define PG8_BAR __builtin_amdgcn_s_barrier()
; #define PG8_SCHED __builtin_amdgcn_sched_barrier(0)
;     DI void operator()(const f32x4 (&acc)[2][2][4][2], const Unit& u, int wr, int wc, int fr, int fq) const {
;         const int row0 = u.pm * BM + wr * 64 + fr, col0 = u.pn * BM + wc * 32 + 8 * fq;
;         f32x4 qa[2][2][2], qb[2][2][2];
; template <class Epi, class Sched, bool ALIGN_EPI = false, bool SP2 = false>
; DI void gemm_phase(LAS unsigned char* lds, const Gemm g, const Sched& S, const Epi& E, const int tidx) {
;     ...
;             PG8_LDA(At, 1, 1); PG8_STAGE(PG8_SB(1, 0), b3, voffB); PG8_STAGE(PG8_SB(1, 1), b3 + hstepB, voffB); PG8_STAGE(PG8_SA(1, 0), a3, voffA);
;             PG8_WAIT_V(8); PG8_WAIT_L(0); PG8_BAR; PG8_MMA(1, 0, At, B0); PG8_MMA(1, 1, At, B1); PG8_BAR; PG8_SCHED;
	s_add_i32 s20, s91, s29
	v_lshl_add_u64 v[202:203], v[202:203], 0, s[92:93]
	s_mov_b32 m0, s20
	ds_read_b128 v[160:163], v229 offset:49152
	ds_read_b128 v[164:167], v229 offset:50176
	ds_read_b128 v[168:171], v229 offset:51200
	ds_read_b128 v[172:175], v229 offset:52224
	ds_read_b128 v[176:179], v229 offset:53248
	ds_read_b128 v[180:183], v229 offset:54272
	ds_read_b128 v[194:197], v229 offset:55296
	ds_read_b128 v[198:201], v229 offset:56320
	global_load_lds_dwordx4 v[202:203], off
	s_add_i32 m0, s20, 0x2000
	s_add_u32 s20, s22, 0x80080
	v_lshl_add_u64 v[202:203], v[206:207], 0, s[92:93]
	s_addc_u32 s21, s23, 0
	s_add_i32 s22, s97, s29
	global_load_lds_dwordx4 v[202:203], off
	v_lshl_add_u64 v[202:203], s[20:21], 0, v[204:205]
	s_mov_b32 m0, s22
	s_nop 0
	global_load_lds_dwordx4 v[202:203], off
	v_lshl_add_u64 v[202:203], s[20:21], 0, v[188:189]
	s_add_i32 m0, s22, 0x2000
	s_nop 0
	global_load_lds_dwordx4 v[202:203], off
	v_lshl_add_u64 v[202:203], v[208:209], 0, s[92:93]
	s_mov_b32 m0, s36
	s_nop 0
	global_load_lds_dwordx4 v[202:203], off
	v_lshl_add_u64 v[202:203], v[222:223], 0, s[92:93]
	s_mov_b32 m0, s37
	s_nop 0
	global_load_lds_dwordx4 v[202:203], off
	s_waitcnt vmcnt(8)
	s_waitcnt lgkmcnt(0)
	s_barrier
	s_setprio 1
	s_waitcnt lgkmcnt(0)
	v_mfma_f32_16x16x32_bf16 v[60:63], v[128:131], v[160:163], v[60:63]
	v_mfma_f32_16x16x32_bf16 v[56:59], v[136:139], v[160:163], v[56:59]
	v_mfma_f32_16x16x32_bf16 v[44:47], v[128:131], v[168:171], v[44:47]
	v_mfma_f32_16x16x32_bf16 v[40:43], v[136:139], v[168:171], v[40:43]
	v_mfma_f32_16x16x32_bf16 v[28:31], v[128:131], v[176:179], v[28:31]
	v_mfma_f32_16x16x32_bf16 v[24:27], v[136:139], v[176:179], v[24:27]
	v_mfma_f32_16x16x32_bf16 v[12:15], v[128:131], v[194:197], v[12:15]
	v_mfma_f32_16x16x32_bf16 v[8:11], v[136:139], v[194:197], v[8:11]
	v_mfma_f32_16x16x32_bf16 v[60:63], v[132:135], v[164:167], v[60:63]
	v_mfma_f32_16x16x32_bf16 v[56:59], v[140:143], v[164:167], v[56:59]
	v_mfma_f32_16x16x32_bf16 v[44:47], v[132:135], v[172:175], v[44:47]
	v_mfma_f32_16x16x32_bf16 v[40:43], v[140:143], v[172:175], v[40:43]
	v_mfma_f32_16x16x32_bf16 v[28:31], v[132:135], v[180:183], v[28:31]
	v_mfma_f32_16x16x32_bf16 v[24:27], v[140:143], v[180:183], v[24:27]
	v_mfma_f32_16x16x32_bf16 v[12:15], v[132:135], v[198:201], v[12:15]
	v_mfma_f32_16x16x32_bf16 v[8:11], v[140:143], v[198:201], v[8:11]
	v_mfma_f32_16x16x32_bf16 v[52:55], v[144:147], v[160:163], v[52:55]
	v_mfma_f32_16x16x32_bf16 v[48:51], v[152:155], v[160:163], v[48:51]
	v_mfma_f32_16x16x32_bf16 v[36:39], v[144:147], v[168:171], v[36:39]
	v_mfma_f32_16x16x32_bf16 v[32:35], v[152:155], v[168:171], v[32:35]
	v_mfma_f32_16x16x32_bf16 v[20:23], v[144:147], v[176:179], v[20:23]
	v_mfma_f32_16x16x32_bf16 v[16:19], v[152:155], v[176:179], v[16:19]
	v_mfma_f32_16x16x32_bf16 v[4:7], v[144:147], v[194:197], v[4:7]
	v_mfma_f32_16x16x32_bf16 v[0:3], v[152:155], v[194:197], v[0:3]
	v_mfma_f32_16x16x32_bf16 v[52:55], v[148:151], v[164:167], v[52:55]
	v_mfma_f32_16x16x32_bf16 v[48:51], v[156:159], v[164:167], v[48:51]
	v_mfma_f32_16x16x32_bf16 v[36:39], v[148:151], v[172:175], v[36:39]
	v_mfma_f32_16x16x32_bf16 v[32:35], v[156:159], v[172:175], v[32:35]
	v_mfma_f32_16x16x32_bf16 v[20:23], v[148:151], v[180:183], v[20:23]
	v_mfma_f32_16x16x32_bf16 v[16:19], v[156:159], v[180:183], v[16:19]
	v_mfma_f32_16x16x32_bf16 v[4:7], v[148:151], v[198:201], v[4:7]
	v_mfma_f32_16x16x32_bf16 v[0:3], v[156:159], v[198:201], v[0:3]
	s_setprio 0
	s_barrier
	s_add_i32 s83, s83, 2
	s_add_u32 s57, s57, 0x100
	s_addc_u32 s82, s82, 0
	s_cmp_gt_u32 s83, 29
	s_mov_b64 s[20:21], s[4:5]
	s_cbranch_scc0 .LBB0_190
	v_lshl_add_u32 v198, s56, 8, v215
	v_lshl_or_b32 v194, s18, 8, v228
	v_ashrrev_i32_e32 v195, 31, v194
	v_ashrrev_i32_e32 v199, 31, v198
	v_lshl_add_u64 v[196:197], v[194:195], 2, s[10:11]
	v_lshlrev_b64 v[128:129], 13, v[198:199]
	v_or_b32_e32 v222, 16, v198
	v_lshl_add_u64 v[128:129], v[196:197], 0, v[128:129]
	v_ashrrev_i32_e32 v223, 31, v222
	global_load_dwordx4 v[230:233], v[128:129], off offset:16
	global_load_dwordx4 v[234:237], v[128:129], off
	global_load_dwordx4 v[176:179], v[128:129], off offset:528
	global_load_dwordx4 v[180:183], v[128:129], off offset:512
	v_lshlrev_b64 v[128:129], 13, v[222:223]
	v_or_b32_e32 v202, 32, v198
	v_lshl_add_u64 v[128:129], v[196:197], 0, v[128:129]
	v_ashrrev_i32_e32 v203, 31, v202
	global_load_dwordx4 v[168:171], v[128:129], off offset:16
	global_load_dwordx4 v[172:175], v[128:129], off
	global_load_dwordx4 v[160:163], v[128:129], off offset:528
	global_load_dwordx4 v[164:167], v[128:129], off offset:512
	v_lshlrev_b64 v[128:129], 13, v[202:203]
	v_or_b32_e32 v200, 48, v198
	v_lshl_add_u64 v[128:129], v[196:197], 0, v[128:129]
	v_ashrrev_i32_e32 v201, 31, v200
	global_load_dwordx4 v[152:155], v[128:129], off offset:16
	global_load_dwordx4 v[156:159], v[128:129], off
	global_load_dwordx4 v[144:147], v[128:129], off offset:528
	global_load_dwordx4 v[148:151], v[128:129], off offset:512
	v_lshlrev_b64 v[128:129], 13, v[200:201]
	v_lshl_add_u64 v[132:133], v[196:197], 0, v[128:129]
	global_load_dwordx4 v[136:139], v[132:133], off offset:16
	global_load_dwordx4 v[140:143], v[132:133], off
	global_load_dwordx4 v[128:131], v[132:133], off offset:528
	s_nop 0
	global_load_dwordx4 v[132:135], v[132:133], off offset:512
	v_lshlrev_b64 v[206:207], 11, v[198:199]
	v_readlane_b32 s18, v253, 45
	v_readlane_b32 s19, v253, 46
	v_lshl_add_u64 v[206:207], v[206:207], 0, v[194:195]
	v_lshl_add_u64 v[224:225], v[206:207], 2, s[8:9]
	v_cndmask_b32_e64 v208, 0, 1, s[18:19]
	s_waitcnt vmcnt(0)
	v_pk_add_f32 v[126:127], v[126:127], v[236:237]
	v_pk_add_f32 v[124:125], v[124:125], v[234:235]
	v_pk_add_f32 v[122:123], v[122:123], v[232:233]
	v_pk_add_f32 v[120:121], v[120:121], v[230:231]
	v_cmp_ne_u32_e64 s[4:5], 1, v208
	s_andn2_b64 vcc, exec, s[18:19]
	v_lshl_add_u64 v[226:227], v[206:207], 1, s[78:79]
	global_store_dwordx4 v[224:225], v[124:127], off
	global_store_dwordx4 v[224:225], v[120:123], off offset:16
	s_cbranch_vccnz .LBB0_193
	v_cvt_pk_bf16_f32 v230, v124, v125
	v_cvt_pk_bf16_f32 v231, v126, v127
	v_cvt_pk_bf16_f32 v232, v120, v121
	v_cvt_pk_bf16_f32 v233, v122, v123
	global_store_dwordx4 v[226:227], v[230:233], off

; #define PG8_STAGE(bufoff, gbase, voff) do { _Pragma("unroll") for (int _i = 0; _i < 2; ++_i) \
;         __builtin_amdgcn_global_load_lds((const unsigned*)((const char*)(gbase) + (voff)[_i]), (LAS unsigned*)(lds + (bufoff) + ldsw + _i * 8192), 16, 0, 0); } while (0)
; #define PG8_LDA(dst, b, h) do { _Pragma("unroll") for (int m = 0; m < 4; ++m) _Pragma("unroll") for (int k = 0; k < 2; ++k) dst[m][k] = *(const LAS bf16x8*)(lds + PG8_SA(b, h) + aoff + m * 2048 + k * 1024); } while (0)
; #define PG8_LDB(dst, b, h) do { _Pragma("unroll") for (int n = 0; n < 2; ++n) _Pragma("unroll") for (int k = 0; k < 2; ++k) dst[n][k] = *(const LAS bf16x8*)(lds + PG8_SB(b, h) + boff + n * 2048 + k * 1024); } while (0)
; #define PG8_MMA(ai, bj, At, Bt) do { __builtin_amdgcn_s_setprio(1); _Pragma("unroll") for (int m = 0; m < 4; ++m) _Pragma("unroll") for (int n = 0; n < 2; ++n) _Pragma("unroll") for (int k = 0; k < 2; ++k) \
;         acc[ai][bj][m][n] = __builtin_amdgcn_mfma_f32_16x16x32_bf16(Bt[n][k], At[m][k], acc[ai][bj][m][n], 0, 0, 0); __builtin_amdgcn_s_setprio(0); } while (0)
; #define PG8_WAIT_V(n) asm volatile("s_waitcnt vmcnt(" #n ")" ::: "memory")
; #define PG8_WAIT_L(n) asm volatile("s_waitcnt lgkmcnt(" #n ")" ::: "memory")
; #define PG8_BAR __builtin_amdgcn_s_barrier()
; #define PG8_SCHED __builtin_amdgcn_sched_barrier(0)
; template <class Epi, class Sched, bool ALIGN_EPI = false, bool SP2 = false>
; DI void gemm_phase(LAS unsigned char* lds, const Gemm g, const Sched& S, const Epi& E, const int tidx) {
;     ...
;             PG8_LDB(B0, 0, 0); PG8_LDB(B1, 0, 1); PG8_SCHED; PG8_LDA(At, 0, 0); PG8_STAGE(PG8_SA(1, 1), a1 + hstepA, voffA);
;             PG8_WAIT_V(8); PG8_WAIT_L(0); PG8_BAR; PG8_MMA(0, 0, At, B0); PG8_MMA(0, 1, At, B1); PG8_BAR; PG8_SCHED;
;             PG8_LDA(At, 0, 1); PG8_STAGE(PG8_SB(0, 0), b2, voffB); PG8_STAGE(PG8_SB(0, 1), b2 + hstepB, voffB); PG8_STAGE(PG8_SA(0, 0), a2, voffA);
;             PG8_WAIT_V(8); PG8_WAIT_L(0); PG8_BAR; PG8_MMA(1, 0, At, B0); PG8_MMA(1, 1, At, B1); PG8_BAR; PG8_SCHED;
.LBB0_504:
	s_add_u32 s28, s26, 0xfff80080
	s_addc_u32 s29, s27, -1
	s_add_i32 s97, 0, 0x10000
	s_cmp_eq_u32 s91, 28
	s_cselect_b32 s31, s17, s29
	s_cselect_b32 s30, s23, s28
	v_add_u32_e32 v148, s97, v151
	s_cselect_b32 s29, s15, s83
	s_cselect_b32 s28, s25, s82
	s_add_i32 s6, 0, 0x14000
	ds_read_b128 v[144:147], v148
	ds_read_b128 v[156:159], v148 offset:1024
	ds_read_b128 v[160:163], v148 offset:2048
	ds_read_b128 v[164:167], v148 offset:3072
	v_add_u32_e32 v148, s6, v151
	ds_read_b128 v[168:171], v148
	ds_read_b128 v[172:175], v148 offset:1024
	ds_read_b128 v[176:179], v148 offset:2048
	ds_read_b128 v[180:183], v148 offset:3072
	v_lshl_add_u64 v[206:207], s[26:27], 0, v[140:141]
	s_add_i32 m0, s37, 0xc000
	ds_read_b128 v[184:187], v155
	ds_read_b128 v[188:191], v155 offset:1024
	ds_read_b128 v[192:195], v155 offset:2048
	ds_read_b128 v[196:199], v155 offset:3072
	ds_read_b128 v[200:203], v155 offset:4096
	ds_read_b128 v[222:225], v155 offset:5120
	ds_read_b128 v[226:229], v155 offset:6144
	ds_read_b128 v[230:233], v155 offset:7168
	global_load_lds_dwordx4 v[206:207], off
	v_lshl_add_u64 v[206:207], s[26:27], 0, v[142:143]
	s_add_i32 m0, s37, 0xe000
	s_nop 0
	global_load_lds_dwordx4 v[206:207], off
	s_waitcnt vmcnt(8)
	s_waitcnt lgkmcnt(0)
	s_barrier
	s_setprio 1
	s_waitcnt lgkmcnt(0)
	v_mfma_f32_16x16x32_bf16 v[68:71], v[144:147], v[184:187], v[68:71]
	v_mfma_f32_16x16x32_bf16 v[56:59], v[160:163], v[184:187], v[56:59]
	v_mfma_f32_16x16x32_bf16 v[52:55], v[144:147], v[192:195], v[52:55]
	v_mfma_f32_16x16x32_bf16 v[48:51], v[160:163], v[192:195], v[48:51]
	v_mfma_f32_16x16x32_bf16 v[44:47], v[144:147], v[200:203], v[44:47]
	v_mfma_f32_16x16x32_bf16 v[40:43], v[160:163], v[200:203], v[40:43]
	v_mfma_f32_16x16x32_bf16 v[36:39], v[144:147], v[226:229], v[36:39]
	v_mfma_f32_16x16x32_bf16 v[32:35], v[160:163], v[226:229], v[32:35]
	v_mfma_f32_16x16x32_bf16 v[68:71], v[156:159], v[188:191], v[68:71]
	v_mfma_f32_16x16x32_bf16 v[56:59], v[164:167], v[188:191], v[56:59]
	v_mfma_f32_16x16x32_bf16 v[52:55], v[156:159], v[196:199], v[52:55]
	v_mfma_f32_16x16x32_bf16 v[48:51], v[164:167], v[196:199], v[48:51]
	v_mfma_f32_16x16x32_bf16 v[44:47], v[156:159], v[222:225], v[44:47]
	v_mfma_f32_16x16x32_bf16 v[40:43], v[164:167], v[222:225], v[40:43]
	v_mfma_f32_16x16x32_bf16 v[36:39], v[156:159], v[230:233], v[36:39]
	v_mfma_f32_16x16x32_bf16 v[32:35], v[164:167], v[230:233], v[32:35]
	v_mfma_f32_16x16x32_bf16 v[124:127], v[168:171], v[184:187], v[124:127]
	v_mfma_f32_16x16x32_bf16 v[120:123], v[176:179], v[184:187], v[120:123]
	v_mfma_f32_16x16x32_bf16 v[116:119], v[168:171], v[192:195], v[116:119]
	v_mfma_f32_16x16x32_bf16 v[112:115], v[176:179], v[192:195], v[112:115]
	v_mfma_f32_16x16x32_bf16 v[108:111], v[168:171], v[200:203], v[108:111]
	v_mfma_f32_16x16x32_bf16 v[104:107], v[176:179], v[200:203], v[104:107]
	v_mfma_f32_16x16x32_bf16 v[100:103], v[168:171], v[226:229], v[100:103]
	v_mfma_f32_16x16x32_bf16 v[96:99], v[176:179], v[226:229], v[96:99]
	v_mfma_f32_16x16x32_bf16 v[124:127], v[172:175], v[188:191], v[124:127]
	v_mfma_f32_16x16x32_bf16 v[120:123], v[180:183], v[188:191], v[120:123]
	v_mfma_f32_16x16x32_bf16 v[116:119], v[172:175], v[196:199], v[116:119]
	v_mfma_f32_16x16x32_bf16 v[112:115], v[180:183], v[196:199], v[112:115]
	v_mfma_f32_16x16x32_bf16 v[108:111], v[172:175], v[222:225], v[108:111]
	v_mfma_f32_16x16x32_bf16 v[104:107], v[180:183], v[222:225], v[104:107]
	v_mfma_f32_16x16x32_bf16 v[100:103], v[172:175], v[230:233], v[100:103]
	v_mfma_f32_16x16x32_bf16 v[96:99], v[180:183], v[230:233], v[96:99]
	s_setprio 0
	s_barrier
	s_add_i32 s7, s97, s36
	v_lshl_add_u64 v[206:207], s[28:29], 0, v[130:131]
	s_mov_b32 m0, s7
	ds_read_b128 v[184:187], v155 offset:16384
	ds_read_b128 v[188:191], v155 offset:17408
	ds_read_b128 v[192:195], v155 offset:18432
	ds_read_b128 v[196:199], v155 offset:19456
	ds_read_b128 v[200:203], v155 offset:20480
	ds_read_b128 v[222:225], v155 offset:21504
	ds_read_b128 v[226:229], v155 offset:22528
	ds_read_b128 v[230:233], v155 offset:23552
	global_load_lds_dwordx4 v[206:207], off
	s_add_i32 m0, s7, 0x2000
	s_add_u32 vcc_lo, s28, 0x80000
	v_lshl_add_u64 v[208:209], s[28:29], 0, v[134:135]
	s_addc_u32 vcc_hi, s29, 0
	s_add_i32 s6, s6, s36
	global_load_lds_dwordx4 v[208:209], off
	v_lshl_add_u64 v[234:235], vcc, 0, v[130:131]
	s_mov_b32 m0, s6
	v_lshl_add_u64 v[236:237], s[30:31], 0, v[132:133]
	global_load_lds_dwordx4 v[234:235], off
	v_lshl_add_u64 v[234:235], vcc, 0, v[134:135]
	s_add_i32 m0, s6, 0x2000
	s_nop 0
	global_load_lds_dwordx4 v[234:235], off
	v_lshl_add_u64 v[234:235], s[30:31], 0, v[128:129]
	s_mov_b32 m0, s37
	s_nop 0
	global_load_lds_dwordx4 v[234:235], off
	s_mov_b32 m0, s38
	s_nop 0
	global_load_lds_dwordx4 v[236:237], off
	s_waitcnt vmcnt(8)
	s_waitcnt lgkmcnt(0)
	s_barrier
; #define PG8_STAGE(bufoff, gbase, voff) do { _Pragma("unroll") for (int _i = 0; _i < 2; ++_i) \
;         __builtin_amdgcn_global_load_lds((const unsigned*)((const char*)(gbase) + (voff)[_i]), (LAS unsigned*)(lds + (bufoff) + ldsw + _i * 8192), 16, 0, 0); } while (0)
; #define PG8_LDA(dst, b, h) do { _Pragma("unroll") for (int m = 0; m < 4; ++m) _Pragma("unroll") for (int k = 0; k < 2; ++k) dst[m][k] = *(const LAS bf16x8*)(lds + PG8_SA(b, h) + aoff + m * 2048 + k * 1024); } while (0)
; #define PG8_LDB(dst, b, h) do { _Pragma("unroll") for (int n = 0; n < 2; ++n) _Pragma("unroll") for (int k = 0; k < 2; ++k) dst[n][k] = *(const LAS bf16x8*)(lds + PG8_SB(b, h) + boff + n * 2048 + k * 1024); } while (0)
; #define PG8_MMA(ai, bj, At, Bt) do { __builtin_amdgcn_s_setprio(1); _Pragma("unroll") for (int m = 0; m < 4; ++m) _Pragma("unroll") for (int n = 0; n < 2; ++n) _Pragma("unroll") for (int k = 0; k < 2; ++k) \
;         acc[ai][bj][m][n] = __builtin_amdgcn_mfma_f32_16x16x32_bf16(Bt[n][k], At[m][k], acc[ai][bj][m][n], 0, 0, 0); __builtin_amdgcn_s_setprio(0); } while (0)
; #define PG8_WAIT_V(n) asm volatile("s_waitcnt vmcnt(" #n ")" ::: "memory")
; #define PG8_WAIT_L(n) asm volatile("s_waitcnt lgkmcnt(" #n ")" ::: "memory")
; #define PG8_BAR __builtin_amdgcn_s_barrier()
; #define PG8_SCHED __builtin_amdgcn_sched_barrier(0)
; template <class Epi, class Sched, bool ALIGN_EPI = false, bool SP2 = false>
; DI void gemm_phase(LAS unsigned char* lds, const Gemm g, const Sched& S, const Epi& E, const int tidx) {
;     ...
;             PG8_WAIT_V(8); PG8_WAIT_L(0); PG8_BAR; PG8_MMA(1, 0, At, B0); PG8_MMA(1, 1, At, B1); PG8_BAR; PG8_SCHED;
;             PG8_LDB(B0, 1, 0); PG8_LDB(B1, 1, 1); PG8_SCHED; PG8_LDA(At, 1, 0); PG8_STAGE(PG8_SA(0, 1), a2 + hstepA, voffA);
;             PG8_WAIT_V(8); PG8_WAIT_L(0); PG8_BAR; PG8_MMA(0, 0, At, B0); PG8_MMA(0, 1, At, B1); PG8_BAR; PG8_SCHED;
;             PG8_LDA(At, 1, 1); PG8_STAGE(PG8_SB(1, 0), b3, voffB); PG8_STAGE(PG8_SB(1, 1), b3 + hstepB, voffB); PG8_STAGE(PG8_SA(1, 0), a3, voffA);
	s_setprio 1
	s_waitcnt lgkmcnt(0)
	v_mfma_f32_16x16x32_bf16 v[28:31], v[144:147], v[184:187], v[28:31]
	v_mfma_f32_16x16x32_bf16 v[24:27], v[160:163], v[184:187], v[24:27]
	v_mfma_f32_16x16x32_bf16 v[20:23], v[144:147], v[192:195], v[20:23]
	v_mfma_f32_16x16x32_bf16 v[16:19], v[160:163], v[192:195], v[16:19]
	v_mfma_f32_16x16x32_bf16 v[12:15], v[144:147], v[200:203], v[12:15]
	v_mfma_f32_16x16x32_bf16 v[8:11], v[160:163], v[200:203], v[8:11]
	v_mfma_f32_16x16x32_bf16 v[4:7], v[144:147], v[226:229], v[4:7]
	v_mfma_f32_16x16x32_bf16 v[0:3], v[160:163], v[226:229], v[0:3]
	v_mfma_f32_16x16x32_bf16 v[28:31], v[156:159], v[188:191], v[28:31]
	v_mfma_f32_16x16x32_bf16 v[24:27], v[164:167], v[188:191], v[24:27]
	v_mfma_f32_16x16x32_bf16 v[20:23], v[156:159], v[196:199], v[20:23]
	v_mfma_f32_16x16x32_bf16 v[16:19], v[164:167], v[196:199], v[16:19]
	v_mfma_f32_16x16x32_bf16 v[12:15], v[156:159], v[222:225], v[12:15]
	v_mfma_f32_16x16x32_bf16 v[8:11], v[164:167], v[222:225], v[8:11]
	v_mfma_f32_16x16x32_bf16 v[4:7], v[156:159], v[230:233], v[4:7]
	v_mfma_f32_16x16x32_bf16 v[0:3], v[164:167], v[230:233], v[0:3]
	v_mfma_f32_16x16x32_bf16 v[92:95], v[168:171], v[184:187], v[92:95]
	v_mfma_f32_16x16x32_bf16 v[88:91], v[176:179], v[184:187], v[88:91]
	v_mfma_f32_16x16x32_bf16 v[84:87], v[168:171], v[192:195], v[84:87]
	v_mfma_f32_16x16x32_bf16 v[80:83], v[176:179], v[192:195], v[80:83]
	v_mfma_f32_16x16x32_bf16 v[76:79], v[168:171], v[200:203], v[76:79]
	v_mfma_f32_16x16x32_bf16 v[72:75], v[176:179], v[200:203], v[72:75]
	v_mfma_f32_16x16x32_bf16 v[64:67], v[168:171], v[226:229], v[64:67]
	v_mfma_f32_16x16x32_bf16 v[60:63], v[176:179], v[226:229], v[60:63]
	v_mfma_f32_16x16x32_bf16 v[92:95], v[172:175], v[188:191], v[92:95]
	v_mfma_f32_16x16x32_bf16 v[88:91], v[180:183], v[188:191], v[88:91]
	v_mfma_f32_16x16x32_bf16 v[84:87], v[172:175], v[196:199], v[84:87]
	v_mfma_f32_16x16x32_bf16 v[80:83], v[180:183], v[196:199], v[80:83]
	v_mfma_f32_16x16x32_bf16 v[76:79], v[172:175], v[222:225], v[76:79]
	v_mfma_f32_16x16x32_bf16 v[72:75], v[180:183], v[222:225], v[72:75]
	v_mfma_f32_16x16x32_bf16 v[64:67], v[172:175], v[230:233], v[64:67]
	v_mfma_f32_16x16x32_bf16 v[60:63], v[180:183], v[230:233], v[60:63]
	s_setprio 0
	s_barrier
	s_add_i32 s6, 0, 0x18000
	v_add_u32_e32 v148, s6, v151
	s_add_i32 s7, 0, 0x1c000
	ds_read_b128 v[144:147], v148
	ds_read_b128 v[156:159], v148 offset:1024
	ds_read_b128 v[160:163], v148 offset:2048
	ds_read_b128 v[164:167], v148 offset:3072
	v_add_u32_e32 v148, s7, v151
	ds_read_b128 v[168:171], v148
	ds_read_b128 v[172:175], v148 offset:1024
	ds_read_b128 v[176:179], v148 offset:2048
	ds_read_b128 v[180:183], v148 offset:3072
	s_add_u32 s30, s30, 0x80000
	s_addc_u32 s31, s31, 0
	s_mov_b32 m0, s39
	v_lshl_add_u64 v[248:249], s[30:31], 0, v[128:129]
	ds_read_b128 v[184:187], v155 offset:32768
	ds_read_b128 v[188:191], v155 offset:33792
	ds_read_b128 v[192:195], v155 offset:34816
	ds_read_b128 v[196:199], v155 offset:35840
	ds_read_b128 v[200:203], v155 offset:36864
	ds_read_b128 v[222:225], v155 offset:37888
	ds_read_b128 v[226:229], v155 offset:38912
	ds_read_b128 v[230:233], v155 offset:39936
	global_load_lds_dwordx4 v[248:249], off
	v_lshl_add_u64 v[248:249], s[30:31], 0, v[132:133]
	s_mov_b32 m0, s50
	s_nop 0
	global_load_lds_dwordx4 v[248:249], off
	s_waitcnt vmcnt(8)
	s_waitcnt lgkmcnt(0)
	s_barrier
	s_setprio 1
	s_waitcnt lgkmcnt(0)
	v_mfma_f32_16x16x32_bf16 v[68:71], v[144:147], v[184:187], v[68:71]
	v_mfma_f32_16x16x32_bf16 v[56:59], v[160:163], v[184:187], v[56:59]
	v_mfma_f32_16x16x32_bf16 v[52:55], v[144:147], v[192:195], v[52:55]
	v_mfma_f32_16x16x32_bf16 v[48:51], v[160:163], v[192:195], v[48:51]
	v_mfma_f32_16x16x32_bf16 v[44:47], v[144:147], v[200:203], v[44:47]
	v_mfma_f32_16x16x32_bf16 v[40:43], v[160:163], v[200:203], v[40:43]
	v_mfma_f32_16x16x32_bf16 v[36:39], v[144:147], v[226:229], v[36:39]
	v_mfma_f32_16x16x32_bf16 v[32:35], v[160:163], v[226:229], v[32:35]
	v_mfma_f32_16x16x32_bf16 v[68:71], v[156:159], v[188:191], v[68:71]
	v_mfma_f32_16x16x32_bf16 v[56:59], v[164:167], v[188:191], v[56:59]
	v_mfma_f32_16x16x32_bf16 v[52:55], v[156:159], v[196:199], v[52:55]
	v_mfma_f32_16x16x32_bf16 v[48:51], v[164:167], v[196:199], v[48:51]
	v_mfma_f32_16x16x32_bf16 v[44:47], v[156:159], v[222:225], v[44:47]
	v_mfma_f32_16x16x32_bf16 v[40:43], v[164:167], v[222:225], v[40:43]
	v_mfma_f32_16x16x32_bf16 v[36:39], v[156:159], v[230:233], v[36:39]
	v_mfma_f32_16x16x32_bf16 v[32:35], v[164:167], v[230:233], v[32:35]
	v_mfma_f32_16x16x32_bf16 v[124:127], v[168:171], v[184:187], v[124:127]
	v_mfma_f32_16x16x32_bf16 v[120:123], v[176:179], v[184:187], v[120:123]
	v_mfma_f32_16x16x32_bf16 v[116:119], v[168:171], v[192:195], v[116:119]
	v_mfma_f32_16x16x32_bf16 v[112:115], v[176:179], v[192:195], v[112:115]
	v_mfma_f32_16x16x32_bf16 v[108:111], v[168:171], v[200:203], v[108:111]
	v_mfma_f32_16x16x32_bf16 v[104:107], v[176:179], v[200:203], v[104:107]
	v_mfma_f32_16x16x32_bf16 v[100:103], v[168:171], v[226:229], v[100:103]
	v_mfma_f32_16x16x32_bf16 v[96:99], v[176:179], v[226:229], v[96:99]
	v_mfma_f32_16x16x32_bf16 v[124:127], v[172:175], v[188:191], v[124:127]
	v_mfma_f32_16x16x32_bf16 v[120:123], v[180:183], v[188:191], v[120:123]
	v_mfma_f32_16x16x32_bf16 v[116:119], v[172:175], v[196:199], v[116:119]
	v_mfma_f32_16x16x32_bf16 v[112:115], v[180:183], v[196:199], v[112:115]
	v_mfma_f32_16x16x32_bf16 v[108:111], v[172:175], v[222:225], v[108:111]
	v_mfma_f32_16x16x32_bf16 v[104:107], v[180:183], v[222:225], v[104:107]
	v_mfma_f32_16x16x32_bf16 v[100:103], v[172:175], v[230:233], v[100:103]
	v_mfma_f32_16x16x32_bf16 v[96:99], v[180:183], v[230:233], v[96:99]
	s_setprio 0
	s_barrier
; #define PG8_STAGE(bufoff, gbase, voff) do { _Pragma("unroll") for (int _i = 0; _i < 2; ++_i) \
;         __builtin_amdgcn_global_load_lds((const unsigned*)((const char*)(gbase) + (voff)[_i]), (LAS unsigned*)(lds + (bufoff) + ldsw + _i * 8192), 16, 0, 0); } while (0)
; #define PG8_LDA(dst, b, h) do { _Pragma("unroll") for (int m = 0; m < 4; ++m) _Pragma("unroll") for (int k = 0; k < 2; ++k) dst[m][k] = *(const LAS bf16x8*)(lds + PG8_SA(b, h) + aoff + m * 2048 + k * 1024); } while (0)
; #define PG8_MMA(ai, bj, At, Bt) do { __builtin_amdgcn_s_setprio(1); _Pragma("unroll") for (int m = 0; m < 4; ++m) _Pragma("unroll") for (int n = 0; n < 2; ++n) _Pragma("unroll") for (int k = 0; k < 2; ++k) \
;         acc[ai][bj][m][n] = __builtin_amdgcn_mfma_f32_16x16x32_bf16(Bt[n][k], At[m][k], acc[ai][bj][m][n], 0, 0, 0); __builtin_amdgcn_s_setprio(0); } while (0)
; #define PG8_WAIT_V(n) asm volatile("s_waitcnt vmcnt(" #n ")" ::: "memory")
; #define PG8_WAIT_L(n) asm volatile("s_waitcnt lgkmcnt(" #n ")" ::: "memory")
; #define PG8_BAR __builtin_amdgcn_s_barrier()
; #define PG8_SCHED __builtin_amdgcn_sched_barrier(0)
; template <class Epi, class Sched, bool ALIGN_EPI = false, bool SP2 = false>
; DI void gemm_phase(LAS unsigned char* lds, const Gemm g, const Sched& S, const Epi& E, const int tidx) {
;     ...
;             PG8_LDA(At, 1, 1); PG8_STAGE(PG8_SB(1, 0), b3, voffB); PG8_STAGE(PG8_SB(1, 1), b3 + hstepB, voffB); PG8_STAGE(PG8_SA(1, 0), a3, voffA);
;             PG8_WAIT_V(8); PG8_WAIT_L(0); PG8_BAR; PG8_MMA(1, 0, At, B0); PG8_MMA(1, 1, At, B1); PG8_BAR; PG8_SCHED;
;     ...
;         if constexpr (ALIGN_EPI) { if (wr == 0) PG8_BAR; }
	s_add_i32 s6, s6, s36
	v_lshl_add_u64 v[206:207], v[206:207], 0, s[92:93]
	s_mov_b32 m0, s6
	ds_read_b128 v[184:187], v155 offset:49152
	ds_read_b128 v[188:191], v155 offset:50176
	ds_read_b128 v[192:195], v155 offset:51200
	ds_read_b128 v[196:199], v155 offset:52224
	ds_read_b128 v[200:203], v155 offset:53248
	ds_read_b128 v[222:225], v155 offset:54272
	ds_read_b128 v[226:229], v155 offset:55296
	ds_read_b128 v[230:233], v155 offset:56320
	global_load_lds_dwordx4 v[206:207], off
	s_add_i32 m0, s6, 0x2000
	s_add_u32 s28, s28, 0x80080
	v_lshl_add_u64 v[206:207], v[208:209], 0, s[92:93]
	s_addc_u32 s29, s29, 0
	s_add_i32 s6, s7, s36
	global_load_lds_dwordx4 v[206:207], off
	v_lshl_add_u64 v[206:207], s[28:29], 0, v[130:131]
	s_mov_b32 m0, s6
	s_nop 0
	global_load_lds_dwordx4 v[206:207], off
	v_lshl_add_u64 v[206:207], s[28:29], 0, v[134:135]
	s_add_i32 m0, s6, 0x2000
	s_nop 0
	global_load_lds_dwordx4 v[206:207], off
	v_lshl_add_u64 v[206:207], v[234:235], 0, s[92:93]
	s_mov_b32 m0, s54
	s_nop 0
	global_load_lds_dwordx4 v[206:207], off
	v_lshl_add_u64 v[206:207], v[236:237], 0, s[92:93]
	s_mov_b32 m0, s55
	s_nop 0
	global_load_lds_dwordx4 v[206:207], off
	s_waitcnt vmcnt(8)
	s_waitcnt lgkmcnt(0)
	s_barrier
	s_setprio 1
	s_waitcnt lgkmcnt(0)
	v_mfma_f32_16x16x32_bf16 v[28:31], v[144:147], v[184:187], v[28:31]
	v_mfma_f32_16x16x32_bf16 v[24:27], v[160:163], v[184:187], v[24:27]
	v_mfma_f32_16x16x32_bf16 v[20:23], v[144:147], v[192:195], v[20:23]
	v_mfma_f32_16x16x32_bf16 v[16:19], v[160:163], v[192:195], v[16:19]
	v_mfma_f32_16x16x32_bf16 v[12:15], v[144:147], v[200:203], v[12:15]
	v_mfma_f32_16x16x32_bf16 v[8:11], v[160:163], v[200:203], v[8:11]
	v_mfma_f32_16x16x32_bf16 v[4:7], v[144:147], v[226:229], v[4:7]
	v_mfma_f32_16x16x32_bf16 v[0:3], v[160:163], v[226:229], v[0:3]
	v_mfma_f32_16x16x32_bf16 v[28:31], v[156:159], v[188:191], v[28:31]
	v_mfma_f32_16x16x32_bf16 v[24:27], v[164:167], v[188:191], v[24:27]
	v_mfma_f32_16x16x32_bf16 v[20:23], v[156:159], v[196:199], v[20:23]
	v_mfma_f32_16x16x32_bf16 v[16:19], v[164:167], v[196:199], v[16:19]
	v_mfma_f32_16x16x32_bf16 v[12:15], v[156:159], v[222:225], v[12:15]
	v_mfma_f32_16x16x32_bf16 v[8:11], v[164:167], v[222:225], v[8:11]
	v_mfma_f32_16x16x32_bf16 v[4:7], v[156:159], v[230:233], v[4:7]
	v_mfma_f32_16x16x32_bf16 v[0:3], v[164:167], v[230:233], v[0:3]
	v_mfma_f32_16x16x32_bf16 v[92:95], v[168:171], v[184:187], v[92:95]
	v_mfma_f32_16x16x32_bf16 v[88:91], v[176:179], v[184:187], v[88:91]
	v_mfma_f32_16x16x32_bf16 v[84:87], v[168:171], v[192:195], v[84:87]
	v_mfma_f32_16x16x32_bf16 v[80:83], v[176:179], v[192:195], v[80:83]
	v_mfma_f32_16x16x32_bf16 v[76:79], v[168:171], v[200:203], v[76:79]
	v_mfma_f32_16x16x32_bf16 v[72:75], v[176:179], v[200:203], v[72:75]
	v_mfma_f32_16x16x32_bf16 v[64:67], v[168:171], v[226:229], v[64:67]
	v_mfma_f32_16x16x32_bf16 v[60:63], v[176:179], v[226:229], v[60:63]
	v_mfma_f32_16x16x32_bf16 v[92:95], v[172:175], v[188:191], v[92:95]
	v_mfma_f32_16x16x32_bf16 v[88:91], v[180:183], v[188:191], v[88:91]
	v_mfma_f32_16x16x32_bf16 v[84:87], v[172:175], v[196:199], v[84:87]
	v_mfma_f32_16x16x32_bf16 v[80:83], v[180:183], v[196:199], v[80:83]
	v_mfma_f32_16x16x32_bf16 v[76:79], v[172:175], v[222:225], v[76:79]
	v_mfma_f32_16x16x32_bf16 v[72:75], v[180:183], v[222:225], v[72:75]
	v_mfma_f32_16x16x32_bf16 v[64:67], v[172:175], v[230:233], v[64:67]
	v_mfma_f32_16x16x32_bf16 v[60:63], v[180:183], v[230:233], v[60:63]
	s_setprio 0
	s_barrier
	s_add_i32 s91, s91, 2
	s_add_u32 s82, s82, 0x100
	s_addc_u32 s83, s83, 0
	s_add_u32 s26, s26, 0x100
	s_addc_u32 s27, s27, 0
	s_cmp_gt_u32 s91, 29
	s_cbranch_scc0 .LBB0_504
	s_and_b64 vcc, exec, s[10:11]
	s_cbranch_vccz .LBB0_507
	s_barrier
